# code placement: one s_nop 0 ahead of the load-segment vmcnt wait where needed so every 32-MFMA run of the five GEMM K-loops starts on an 8-byte boundary (8 pads)
# speedup vs baseline: 1.0038x; 1.0038x over previous
; #define PG8_STAGE(bufoff, gbase, voff) do { _Pragma("unroll") for (int _i = 0; _i < 2; ++_i) \
;         __builtin_amdgcn_global_load_lds((const unsigned*)((const char*)(gbase) + (voff)[_i]), (LAS unsigned*)(lds + (bufoff) + ldsw + _i * 8192), 16, 0, 0); } while (0)
; #define PG8_LDA(dst, b, h) do { _Pragma("unroll") for (int m = 0; m < 4; ++m) _Pragma("unroll") for (int k = 0; k < 2; ++k) dst[m][k] = *(const LAS bf16x8*)(lds + PG8_SA(b, h) + aoff + m * 2048 + k * 1024); } while (0)
; #define PG8_LDB(dst, b, h) do { _Pragma("unroll") for (int n = 0; n < 2; ++n) _Pragma("unroll") for (int k = 0; k < 2; ++k) dst[n][k] = *(const LAS bf16x8*)(lds + PG8_SB(b, h) + boff + n * 2048 + k * 1024); } while (0)
; #define PG8_MMA(ai, bj, At, Bt) do { __builtin_amdgcn_s_setprio(1); _Pragma("unroll") for (int m = 0; m < 4; ++m) _Pragma("unroll") for (int n = 0; n < 2; ++n) _Pragma("unroll") for (int k = 0; k < 2; ++k) \
;         acc[ai][bj][m][n] = __builtin_amdgcn_mfma_f32_16x16x32_bf16(Bt[n][k], At[m][k], acc[ai][bj][m][n], 0, 0, 0); __builtin_amdgcn_s_setprio(0); } while (0)
; #define PG8_WAIT_V(n) asm volatile("s_waitcnt vmcnt(" #n ")" ::: "memory")
; #define PG8_WAIT_L(n) asm volatile("s_waitcnt lgkmcnt(" #n ")" ::: "memory")
; #define PG8_BAR __builtin_amdgcn_s_barrier()
; #define PG8_SCHED __builtin_amdgcn_sched_barrier(0)
; template <class Epi, bool ALIGN_EPI>
; __device__ __forceinline__ void gemm_phase(LAS unsigned char* lds, const int tid, const Gemm g, const StaticOrder& S, const Epi& E) {
;     ...
;             const bool last = (t == nt - 2);
;             const char* a1 = cA + (size_t)(t + 1) * kstepA;
;             const char* a2 = last ? nA : cA + (size_t)(t + 2) * kstepA; const char* b2 = last ? nB : cB + (size_t)(t + 2) * kstepB;
;             const char* a3 = a2 + kstepA; const char* b3 = b2 + kstepB;
;             PG8_LDB(B0, 0, 0); PG8_LDB(B1, 0, 1); PG8_SCHED; PG8_LDA(At, 0, 0); PG8_STAGE(PG8_SA(1, 1), a1 + hstepA, voffA);
;             PG8_WAIT_V(8); PG8_WAIT_L(0); PG8_BAR; PG8_MMA(0, 0, At, B0); PG8_MMA(0, 1, At, B1); PG8_BAR; PG8_SCHED;
;             PG8_LDA(At, 0, 1); PG8_STAGE(PG8_SB(0, 0), b2, voffB); PG8_STAGE(PG8_SB(0, 1), b2 + hstepB, voffB); PG8_STAGE(PG8_SA(0, 0), a2, voffA);
;             PG8_WAIT_V(8); PG8_WAIT_L(0); PG8_BAR; PG8_MMA(1, 0, At, B0); PG8_MMA(1, 1, At, B1); PG8_BAR; PG8_SCHED;
.LBB0_113:
	s_add_i32 s90, s90, 2
	s_and_b64 s[34:35], exec, s[34:35]
	s_cselect_b32 s55, s23, s27
	s_cselect_b32 s54, s22, s25
	s_add_u32 s34, s92, 0x120000
	s_addc_u32 s35, s93, 0
	s_add_i32 s91, 0, 0x10000
	s_add_i32 s96, 0, 0x14000
	v_add_u32_e32 v148, s91, v175
	v_add_u32_e32 v164, s96, v175
	ds_read_b128 v[136:139], v148
	ds_read_b128 v[140:143], v148 offset:1024
	ds_read_b128 v[144:147], v148 offset:2048
	ds_read_b128 v[148:151], v148 offset:3072
	ds_read_b128 v[152:155], v164
	ds_read_b128 v[156:159], v164 offset:1024
	ds_read_b128 v[160:163], v164 offset:2048
	ds_read_b128 v[164:167], v164 offset:3072
	v_lshl_add_u64 v[172:173], s[30:31], 0, v[134:135]
	s_add_i32 m0, s56, 0xc000
	ds_read_b128 v[168:171], v177
	ds_read_b128 v[178:181], v177 offset:1024
	ds_read_b128 v[182:185], v177 offset:2048
	ds_read_b128 v[186:189], v177 offset:3072
	ds_read_b128 v[190:193], v177 offset:4096
	ds_read_b128 v[210:213], v177 offset:5120
	ds_read_b128 v[214:217], v177 offset:6144
	ds_read_b128 v[218:221], v177 offset:7168
	global_load_lds_dwordx4 v[172:173], off
	v_lshl_add_u64 v[172:173], s[30:31], 0, v[132:133]
	s_add_i32 m0, s56, 0xe000
	s_nop 0
	global_load_lds_dwordx4 v[172:173], off
	s_sub_u32 s98, s30, 0x4000
	s_subb_u32 s99, s31, 0
	v_lshl_add_u64 v[172:173], s[98:99], 0, v[134:135]
	s_mov_b32 m0, s70
	s_nop 0
	global_load_lds_dwordx4 v[172:173], off
	v_lshl_add_u64 v[172:173], s[98:99], 0, v[132:133]
	s_mov_b32 m0, s71
	s_nop 0
	global_load_lds_dwordx4 v[172:173], off
	s_waitcnt vmcnt(8)
	s_waitcnt lgkmcnt(0)
	s_barrier
	v_mfma_f32_16x16x32_bf16 v[126:129], v[136:139], v[168:171], v[126:129]
	v_mfma_f32_16x16x32_bf16 v[94:97], v[144:147], v[168:171], v[94:97]
	v_mfma_f32_16x16x32_bf16 v[122:125], v[136:139], v[182:185], v[122:125]
	v_mfma_f32_16x16x32_bf16 v[90:93], v[144:147], v[182:185], v[90:93]
	v_mfma_f32_16x16x32_bf16 v[118:121], v[136:139], v[190:193], v[118:121]
	v_mfma_f32_16x16x32_bf16 v[86:89], v[144:147], v[190:193], v[86:89]
	v_mfma_f32_16x16x32_bf16 v[114:117], v[136:139], v[214:217], v[114:117]
	v_mfma_f32_16x16x32_bf16 v[82:85], v[144:147], v[214:217], v[82:85]
	v_mfma_f32_16x16x32_bf16 v[126:129], v[140:143], v[178:181], v[126:129]
	v_mfma_f32_16x16x32_bf16 v[94:97], v[148:151], v[178:181], v[94:97]
	v_mfma_f32_16x16x32_bf16 v[122:125], v[140:143], v[186:189], v[122:125]
	v_mfma_f32_16x16x32_bf16 v[90:93], v[148:151], v[186:189], v[90:93]
	v_mfma_f32_16x16x32_bf16 v[118:121], v[140:143], v[210:213], v[118:121]
	v_mfma_f32_16x16x32_bf16 v[86:89], v[148:151], v[210:213], v[86:89]
	v_mfma_f32_16x16x32_bf16 v[114:117], v[140:143], v[218:221], v[114:117]
	v_mfma_f32_16x16x32_bf16 v[82:85], v[148:151], v[218:221], v[82:85]
	v_mfma_f32_16x16x32_bf16 v[62:65], v[152:155], v[168:171], v[62:65]
	v_mfma_f32_16x16x32_bf16 v[38:41], v[160:163], v[168:171], v[38:41]
	v_mfma_f32_16x16x32_bf16 v[58:61], v[152:155], v[182:185], v[58:61]
	v_mfma_f32_16x16x32_bf16 v[30:33], v[160:163], v[182:185], v[30:33]
	v_mfma_f32_16x16x32_bf16 v[54:57], v[152:155], v[190:193], v[54:57]
	v_mfma_f32_16x16x32_bf16 v[22:25], v[160:163], v[190:193], v[22:25]
	v_mfma_f32_16x16x32_bf16 v[50:53], v[152:155], v[214:217], v[50:53]
	v_mfma_f32_16x16x32_bf16 v[18:21], v[160:163], v[214:217], v[18:21]
	v_mfma_f32_16x16x32_bf16 v[62:65], v[156:159], v[178:181], v[62:65]
	v_mfma_f32_16x16x32_bf16 v[38:41], v[164:167], v[178:181], v[38:41]
	v_mfma_f32_16x16x32_bf16 v[58:61], v[156:159], v[186:189], v[58:61]
	v_mfma_f32_16x16x32_bf16 v[30:33], v[164:167], v[186:189], v[30:33]
	v_mfma_f32_16x16x32_bf16 v[54:57], v[156:159], v[210:213], v[54:57]
	v_mfma_f32_16x16x32_bf16 v[22:25], v[164:167], v[210:213], v[22:25]
	v_mfma_f32_16x16x32_bf16 v[50:53], v[156:159], v[218:221], v[50:53]
	v_mfma_f32_16x16x32_bf16 v[18:21], v[164:167], v[218:221], v[18:21]
	s_barrier
	s_add_i32 s91, s91, s29
	v_lshl_add_u64 v[172:173], s[54:55], 0, v[0:1]
	s_mov_b32 m0, s91
	ds_read_b128 v[168:171], v177 offset:16384
	ds_read_b128 v[178:181], v177 offset:17408
	ds_read_b128 v[182:185], v177 offset:18432
	ds_read_b128 v[186:189], v177 offset:19456
	ds_read_b128 v[190:193], v177 offset:20480
	ds_read_b128 v[210:213], v177 offset:21504
	ds_read_b128 v[214:217], v177 offset:22528
	ds_read_b128 v[218:221], v177 offset:23552
	global_load_lds_dwordx4 v[172:173], off
	s_add_i32 m0, s91, 0x2000
	s_add_u32 s94, s54, 0x4000
	v_lshl_add_u64 v[172:173], s[54:55], 0, v[130:131]
	s_addc_u32 s95, s55, 0
	s_add_i32 s91, s96, s29
	global_load_lds_dwordx4 v[172:173], off
	v_lshl_add_u64 v[172:173], s[94:95], 0, v[0:1]
	s_mov_b32 m0, s91
	s_nop 0
	global_load_lds_dwordx4 v[172:173], off
	v_lshl_add_u64 v[172:173], s[94:95], 0, v[130:131]
	s_add_i32 m0, s91, 0x2000
	s_nop 0
	global_load_lds_dwordx4 v[172:173], off
	s_nop 0
	s_waitcnt vmcnt(4)
	s_waitcnt lgkmcnt(0)
	s_barrier
; #define PG8_STAGE(bufoff, gbase, voff) do { _Pragma("unroll") for (int _i = 0; _i < 2; ++_i) \
;         __builtin_amdgcn_global_load_lds((const unsigned*)((const char*)(gbase) + (voff)[_i]), (LAS unsigned*)(lds + (bufoff) + ldsw + _i * 8192), 16, 0, 0); } while (0)
; #define PG8_LDA(dst, b, h) do { _Pragma("unroll") for (int m = 0; m < 4; ++m) _Pragma("unroll") for (int k = 0; k < 2; ++k) dst[m][k] = *(const LAS bf16x8*)(lds + PG8_SA(b, h) + aoff + m * 2048 + k * 1024); } while (0)
; #define PG8_LDB(dst, b, h) do { _Pragma("unroll") for (int n = 0; n < 2; ++n) _Pragma("unroll") for (int k = 0; k < 2; ++k) dst[n][k] = *(const LAS bf16x8*)(lds + PG8_SB(b, h) + boff + n * 2048 + k * 1024); } while (0)
; #define PG8_MMA(ai, bj, At, Bt) do { __builtin_amdgcn_s_setprio(1); _Pragma("unroll") for (int m = 0; m < 4; ++m) _Pragma("unroll") for (int n = 0; n < 2; ++n) _Pragma("unroll") for (int k = 0; k < 2; ++k) \
;         acc[ai][bj][m][n] = __builtin_amdgcn_mfma_f32_16x16x32_bf16(Bt[n][k], At[m][k], acc[ai][bj][m][n], 0, 0, 0); __builtin_amdgcn_s_setprio(0); } while (0)
; #define PG8_WAIT_V(n) asm volatile("s_waitcnt vmcnt(" #n ")" ::: "memory")
; #define PG8_WAIT_L(n) asm volatile("s_waitcnt lgkmcnt(" #n ")" ::: "memory")
; #define PG8_BAR __builtin_amdgcn_s_barrier()
; #define PG8_SCHED __builtin_amdgcn_sched_barrier(0)
; template <class Epi, bool ALIGN_EPI>
; __device__ __forceinline__ void gemm_phase(LAS unsigned char* lds, const int tid, const Gemm g, const StaticOrder& S, const Epi& E) {
;     ...
;             PG8_WAIT_V(8); PG8_WAIT_L(0); PG8_BAR; PG8_MMA(1, 0, At, B0); PG8_MMA(1, 1, At, B1); PG8_BAR; PG8_SCHED;
;             PG8_LDB(B0, 1, 0); PG8_LDB(B1, 1, 1); PG8_SCHED; PG8_LDA(At, 1, 0); PG8_STAGE(PG8_SA(0, 1), a2 + hstepA, voffA);
;             PG8_WAIT_V(8); PG8_WAIT_L(0); PG8_BAR; PG8_MMA(0, 0, At, B0); PG8_MMA(0, 1, At, B1); PG8_BAR; PG8_SCHED;
	v_mfma_f32_16x16x32_bf16 v[110:113], v[136:139], v[168:171], v[110:113]
	v_mfma_f32_16x16x32_bf16 v[78:81], v[144:147], v[168:171], v[78:81]
	v_mfma_f32_16x16x32_bf16 v[106:109], v[136:139], v[182:185], v[106:109]
	v_mfma_f32_16x16x32_bf16 v[74:77], v[144:147], v[182:185], v[74:77]
	v_mfma_f32_16x16x32_bf16 v[102:105], v[136:139], v[190:193], v[102:105]
	v_mfma_f32_16x16x32_bf16 v[70:73], v[144:147], v[190:193], v[70:73]
	v_mfma_f32_16x16x32_bf16 v[98:101], v[136:139], v[214:217], v[98:101]
	v_mfma_f32_16x16x32_bf16 v[66:69], v[144:147], v[214:217], v[66:69]
	v_mfma_f32_16x16x32_bf16 v[110:113], v[140:143], v[178:181], v[110:113]
	v_mfma_f32_16x16x32_bf16 v[78:81], v[148:151], v[178:181], v[78:81]
	v_mfma_f32_16x16x32_bf16 v[106:109], v[140:143], v[186:189], v[106:109]
	v_mfma_f32_16x16x32_bf16 v[74:77], v[148:151], v[186:189], v[74:77]
	v_mfma_f32_16x16x32_bf16 v[102:105], v[140:143], v[210:213], v[102:105]
	v_mfma_f32_16x16x32_bf16 v[70:73], v[148:151], v[210:213], v[70:73]
	v_mfma_f32_16x16x32_bf16 v[98:101], v[140:143], v[218:221], v[98:101]
	v_mfma_f32_16x16x32_bf16 v[66:69], v[148:151], v[218:221], v[66:69]
	v_mfma_f32_16x16x32_bf16 v[46:49], v[152:155], v[168:171], v[46:49]
	v_mfma_f32_16x16x32_bf16 v[14:17], v[160:163], v[168:171], v[14:17]
	v_mfma_f32_16x16x32_bf16 v[42:45], v[152:155], v[182:185], v[42:45]
	v_mfma_f32_16x16x32_bf16 v[10:13], v[160:163], v[182:185], v[10:13]
	v_mfma_f32_16x16x32_bf16 v[34:37], v[152:155], v[190:193], v[34:37]
	v_mfma_f32_16x16x32_bf16 v[6:9], v[160:163], v[190:193], v[6:9]
	v_mfma_f32_16x16x32_bf16 v[26:29], v[152:155], v[214:217], v[26:29]
	v_mfma_f32_16x16x32_bf16 v[2:5], v[160:163], v[214:217], v[2:5]
	v_mfma_f32_16x16x32_bf16 v[46:49], v[156:159], v[178:181], v[46:49]
	v_mfma_f32_16x16x32_bf16 v[14:17], v[164:167], v[178:181], v[14:17]
	v_mfma_f32_16x16x32_bf16 v[42:45], v[156:159], v[186:189], v[42:45]
	v_mfma_f32_16x16x32_bf16 v[10:13], v[164:167], v[186:189], v[10:13]
	v_mfma_f32_16x16x32_bf16 v[34:37], v[156:159], v[210:213], v[34:37]
	v_mfma_f32_16x16x32_bf16 v[6:9], v[164:167], v[210:213], v[6:9]
	v_mfma_f32_16x16x32_bf16 v[26:29], v[156:159], v[218:221], v[26:29]
	v_mfma_f32_16x16x32_bf16 v[2:5], v[164:167], v[218:221], v[2:5]
	s_barrier
	s_add_i32 s91, 0, 0x18000
	s_add_i32 s94, 0, 0x1c000
	v_add_u32_e32 v148, s91, v175
	v_add_u32_e32 v164, s94, v175
	ds_read_b128 v[136:139], v148
	ds_read_b128 v[140:143], v148 offset:1024
	ds_read_b128 v[144:147], v148 offset:2048
	ds_read_b128 v[148:151], v148 offset:3072
	ds_read_b128 v[152:155], v164
	ds_read_b128 v[156:159], v164 offset:1024
	ds_read_b128 v[160:163], v164 offset:2048
	ds_read_b128 v[164:167], v164 offset:3072
	v_lshl_add_u64 v[172:173], s[92:93], 0, v[0:1]
	s_mov_b32 m0, s56
	s_nop 0
	global_load_lds_dwordx4 v[172:173], off
	v_lshl_add_u64 v[172:173], s[92:93], 0, v[130:131]
	s_mov_b32 m0, s58
	s_nop 0
	global_load_lds_dwordx4 v[172:173], off
	s_add_u32 s92, s92, 0x4000
	s_addc_u32 s93, s93, 0
	s_mov_b32 m0, s63
	v_lshl_add_u64 v[172:173], s[92:93], 0, v[0:1]
	ds_read_b128 v[168:171], v177 offset:32768
	ds_read_b128 v[178:181], v177 offset:33792
	ds_read_b128 v[182:185], v177 offset:34816
	ds_read_b128 v[186:189], v177 offset:35840
	ds_read_b128 v[190:193], v177 offset:36864
	ds_read_b128 v[210:213], v177 offset:37888
	ds_read_b128 v[214:217], v177 offset:38912
	ds_read_b128 v[218:221], v177 offset:39936
	global_load_lds_dwordx4 v[172:173], off
	v_lshl_add_u64 v[172:173], s[92:93], 0, v[130:131]
	s_mov_b32 m0, s64
	s_nop 0
	global_load_lds_dwordx4 v[172:173], off
	s_waitcnt vmcnt(8)
	s_waitcnt lgkmcnt(0)
	s_barrier
; #define PG8_STAGE(bufoff, gbase, voff) do { _Pragma("unroll") for (int _i = 0; _i < 2; ++_i) \
;         __builtin_amdgcn_global_load_lds((const unsigned*)((const char*)(gbase) + (voff)[_i]), (LAS unsigned*)(lds + (bufoff) + ldsw + _i * 8192), 16, 0, 0); } while (0)
; #define PG8_LDA(dst, b, h) do { _Pragma("unroll") for (int m = 0; m < 4; ++m) _Pragma("unroll") for (int k = 0; k < 2; ++k) dst[m][k] = *(const LAS bf16x8*)(lds + PG8_SA(b, h) + aoff + m * 2048 + k * 1024); } while (0)
; #define PG8_MMA(ai, bj, At, Bt) do { __builtin_amdgcn_s_setprio(1); _Pragma("unroll") for (int m = 0; m < 4; ++m) _Pragma("unroll") for (int n = 0; n < 2; ++n) _Pragma("unroll") for (int k = 0; k < 2; ++k) \
;         acc[ai][bj][m][n] = __builtin_amdgcn_mfma_f32_16x16x32_bf16(Bt[n][k], At[m][k], acc[ai][bj][m][n], 0, 0, 0); __builtin_amdgcn_s_setprio(0); } while (0)
; #define PG8_WAIT_V(n) asm volatile("s_waitcnt vmcnt(" #n ")" ::: "memory")
; #define PG8_WAIT_L(n) asm volatile("s_waitcnt lgkmcnt(" #n ")" ::: "memory")
; #define PG8_BAR __builtin_amdgcn_s_barrier()
; #define PG8_SCHED __builtin_amdgcn_sched_barrier(0)
; template <class Epi, bool ALIGN_EPI>
; __device__ __forceinline__ void gemm_phase(LAS unsigned char* lds, const int tid, const Gemm g, const StaticOrder& S, const Epi& E) {
;     ...
;             PG8_WAIT_V(8); PG8_WAIT_L(0); PG8_BAR; PG8_MMA(0, 0, At, B0); PG8_MMA(0, 1, At, B1); PG8_BAR; PG8_SCHED;
;             PG8_LDA(At, 1, 1); PG8_STAGE(PG8_SB(1, 0), b3, voffB); PG8_STAGE(PG8_SB(1, 1), b3 + hstepB, voffB); PG8_STAGE(PG8_SA(1, 0), a3, voffA);
;             PG8_WAIT_V(8); PG8_WAIT_L(0); PG8_BAR; PG8_MMA(1, 0, At, B0); PG8_MMA(1, 1, At, B1); PG8_BAR; PG8_SCHED;
;         }
	v_mfma_f32_16x16x32_bf16 v[126:129], v[136:139], v[168:171], v[126:129]
	v_mfma_f32_16x16x32_bf16 v[94:97], v[144:147], v[168:171], v[94:97]
	v_mfma_f32_16x16x32_bf16 v[122:125], v[136:139], v[182:185], v[122:125]
	v_mfma_f32_16x16x32_bf16 v[90:93], v[144:147], v[182:185], v[90:93]
	v_mfma_f32_16x16x32_bf16 v[118:121], v[136:139], v[190:193], v[118:121]
	v_mfma_f32_16x16x32_bf16 v[86:89], v[144:147], v[190:193], v[86:89]
	v_mfma_f32_16x16x32_bf16 v[114:117], v[136:139], v[214:217], v[114:117]
	v_mfma_f32_16x16x32_bf16 v[82:85], v[144:147], v[214:217], v[82:85]
	v_mfma_f32_16x16x32_bf16 v[126:129], v[140:143], v[178:181], v[126:129]
	v_mfma_f32_16x16x32_bf16 v[94:97], v[148:151], v[178:181], v[94:97]
	v_mfma_f32_16x16x32_bf16 v[122:125], v[140:143], v[186:189], v[122:125]
	v_mfma_f32_16x16x32_bf16 v[90:93], v[148:151], v[186:189], v[90:93]
	v_mfma_f32_16x16x32_bf16 v[118:121], v[140:143], v[210:213], v[118:121]
	v_mfma_f32_16x16x32_bf16 v[86:89], v[148:151], v[210:213], v[86:89]
	v_mfma_f32_16x16x32_bf16 v[114:117], v[140:143], v[218:221], v[114:117]
	v_mfma_f32_16x16x32_bf16 v[82:85], v[148:151], v[218:221], v[82:85]
	v_mfma_f32_16x16x32_bf16 v[62:65], v[152:155], v[168:171], v[62:65]
	v_mfma_f32_16x16x32_bf16 v[38:41], v[160:163], v[168:171], v[38:41]
	v_mfma_f32_16x16x32_bf16 v[58:61], v[152:155], v[182:185], v[58:61]
	v_mfma_f32_16x16x32_bf16 v[30:33], v[160:163], v[182:185], v[30:33]
	v_mfma_f32_16x16x32_bf16 v[54:57], v[152:155], v[190:193], v[54:57]
	v_mfma_f32_16x16x32_bf16 v[22:25], v[160:163], v[190:193], v[22:25]
	v_mfma_f32_16x16x32_bf16 v[50:53], v[152:155], v[214:217], v[50:53]
	v_mfma_f32_16x16x32_bf16 v[18:21], v[160:163], v[214:217], v[18:21]
	v_mfma_f32_16x16x32_bf16 v[62:65], v[156:159], v[178:181], v[62:65]
	v_mfma_f32_16x16x32_bf16 v[38:41], v[164:167], v[178:181], v[38:41]
	v_mfma_f32_16x16x32_bf16 v[58:61], v[156:159], v[186:189], v[58:61]
	v_mfma_f32_16x16x32_bf16 v[30:33], v[164:167], v[186:189], v[30:33]
	v_mfma_f32_16x16x32_bf16 v[54:57], v[156:159], v[210:213], v[54:57]
	v_mfma_f32_16x16x32_bf16 v[22:25], v[164:167], v[210:213], v[22:25]
	v_mfma_f32_16x16x32_bf16 v[50:53], v[156:159], v[218:221], v[50:53]
	v_mfma_f32_16x16x32_bf16 v[18:21], v[164:167], v[218:221], v[18:21]
	s_barrier
	s_add_u32 s92, s54, 0x40000
	s_addc_u32 s93, s55, 0
	s_add_i32 s91, s91, s29
	v_lshl_add_u64 v[172:173], s[92:93], 0, v[0:1]
	s_mov_b32 m0, s91
	ds_read_b128 v[168:171], v177 offset:49152
	ds_read_b128 v[178:181], v177 offset:50176
	ds_read_b128 v[182:185], v177 offset:51200
	ds_read_b128 v[186:189], v177 offset:52224
	ds_read_b128 v[190:193], v177 offset:53248
	ds_read_b128 v[210:213], v177 offset:54272
	ds_read_b128 v[214:217], v177 offset:55296
	ds_read_b128 v[218:221], v177 offset:56320
	global_load_lds_dwordx4 v[172:173], off
	s_add_i32 m0, s91, 0x2000
	s_add_u32 s54, s54, 0x44000
	v_lshl_add_u64 v[172:173], s[92:93], 0, v[130:131]
	s_addc_u32 s55, s55, 0
	s_add_i32 s91, s94, s29
	global_load_lds_dwordx4 v[172:173], off
	v_lshl_add_u64 v[172:173], s[54:55], 0, v[0:1]
	s_mov_b32 m0, s91
	s_nop 0
	global_load_lds_dwordx4 v[172:173], off
	v_lshl_add_u64 v[172:173], s[54:55], 0, v[130:131]
	s_add_i32 m0, s91, 0x2000
	s_nop 0
	global_load_lds_dwordx4 v[172:173], off
	s_waitcnt vmcnt(4)
	s_waitcnt lgkmcnt(0)
	s_barrier
	v_mfma_f32_16x16x32_bf16 v[110:113], v[136:139], v[168:171], v[110:113]
	v_mfma_f32_16x16x32_bf16 v[78:81], v[144:147], v[168:171], v[78:81]
	v_mfma_f32_16x16x32_bf16 v[106:109], v[136:139], v[182:185], v[106:109]
	v_mfma_f32_16x16x32_bf16 v[74:77], v[144:147], v[182:185], v[74:77]
	v_mfma_f32_16x16x32_bf16 v[102:105], v[136:139], v[190:193], v[102:105]
	v_mfma_f32_16x16x32_bf16 v[70:73], v[144:147], v[190:193], v[70:73]
	v_mfma_f32_16x16x32_bf16 v[98:101], v[136:139], v[214:217], v[98:101]
	v_mfma_f32_16x16x32_bf16 v[66:69], v[144:147], v[214:217], v[66:69]
	v_mfma_f32_16x16x32_bf16 v[110:113], v[140:143], v[178:181], v[110:113]
	v_mfma_f32_16x16x32_bf16 v[78:81], v[148:151], v[178:181], v[78:81]
	v_mfma_f32_16x16x32_bf16 v[106:109], v[140:143], v[186:189], v[106:109]
	v_mfma_f32_16x16x32_bf16 v[74:77], v[148:151], v[186:189], v[74:77]
	v_mfma_f32_16x16x32_bf16 v[102:105], v[140:143], v[210:213], v[102:105]
	v_mfma_f32_16x16x32_bf16 v[70:73], v[148:151], v[210:213], v[70:73]
	v_mfma_f32_16x16x32_bf16 v[98:101], v[140:143], v[218:221], v[98:101]
	v_mfma_f32_16x16x32_bf16 v[66:69], v[148:151], v[218:221], v[66:69]
	v_mfma_f32_16x16x32_bf16 v[46:49], v[152:155], v[168:171], v[46:49]
	v_mfma_f32_16x16x32_bf16 v[14:17], v[160:163], v[168:171], v[14:17]
	v_mfma_f32_16x16x32_bf16 v[42:45], v[152:155], v[182:185], v[42:45]
	v_mfma_f32_16x16x32_bf16 v[10:13], v[160:163], v[182:185], v[10:13]
	v_mfma_f32_16x16x32_bf16 v[34:37], v[152:155], v[190:193], v[34:37]
	v_mfma_f32_16x16x32_bf16 v[6:9], v[160:163], v[190:193], v[6:9]
	v_mfma_f32_16x16x32_bf16 v[26:29], v[152:155], v[214:217], v[26:29]
	v_mfma_f32_16x16x32_bf16 v[2:5], v[160:163], v[214:217], v[2:5]
	v_mfma_f32_16x16x32_bf16 v[46:49], v[156:159], v[178:181], v[46:49]
	v_mfma_f32_16x16x32_bf16 v[14:17], v[164:167], v[178:181], v[14:17]
	v_mfma_f32_16x16x32_bf16 v[42:45], v[156:159], v[186:189], v[42:45]
	v_mfma_f32_16x16x32_bf16 v[10:13], v[164:167], v[186:189], v[10:13]
	v_mfma_f32_16x16x32_bf16 v[34:37], v[156:159], v[210:213], v[34:37]
	v_mfma_f32_16x16x32_bf16 v[6:9], v[164:167], v[210:213], v[6:9]
	v_mfma_f32_16x16x32_bf16 v[26:29], v[156:159], v[218:221], v[26:29]
	v_mfma_f32_16x16x32_bf16 v[2:5], v[164:167], v[218:221], v[2:5]
	s_barrier
	s_add_u32 s25, s25, 0x80000
	s_addc_u32 s27, s27, 0
	s_add_u32 s30, s30, 0x240000
	s_addc_u32 s31, s31, 0
	s_cmp_ge_u32 s90, s17
	s_cbranch_scc1 .LBB0_116

; #define PG8_STAGE(bufoff, gbase, voff) do { _Pragma("unroll") for (int _i = 0; _i < 2; ++_i) \
;         __builtin_amdgcn_global_load_lds((const unsigned*)((const char*)(gbase) + (voff)[_i]), (LAS unsigned*)(lds + (bufoff) + ldsw + _i * 8192), 16, 0, 0); } while (0)
; #define PG8_LDA(dst, b, h) do { _Pragma("unroll") for (int m = 0; m < 4; ++m) _Pragma("unroll") for (int k = 0; k < 2; ++k) dst[m][k] = *(const LAS bf16x8*)(lds + PG8_SA(b, h) + aoff + m * 2048 + k * 1024); } while (0)
; #define PG8_LDB(dst, b, h) do { _Pragma("unroll") for (int n = 0; n < 2; ++n) _Pragma("unroll") for (int k = 0; k < 2; ++k) dst[n][k] = *(const LAS bf16x8*)(lds + PG8_SB(b, h) + boff + n * 2048 + k * 1024); } while (0)
; #define PG8_MMA(ai, bj, At, Bt) do { __builtin_amdgcn_s_setprio(1); _Pragma("unroll") for (int m = 0; m < 4; ++m) _Pragma("unroll") for (int n = 0; n < 2; ++n) _Pragma("unroll") for (int k = 0; k < 2; ++k) \
;         acc[ai][bj][m][n] = __builtin_amdgcn_mfma_f32_16x16x32_bf16(Bt[n][k], At[m][k], acc[ai][bj][m][n], 0, 0, 0); __builtin_amdgcn_s_setprio(0); } while (0)
; #define PG8_WAIT_V(n) asm volatile("s_waitcnt vmcnt(" #n ")" ::: "memory")
; #define PG8_WAIT_L(n) asm volatile("s_waitcnt lgkmcnt(" #n ")" ::: "memory")
; #define PG8_BAR __builtin_amdgcn_s_barrier()
; #define PG8_SCHED __builtin_amdgcn_sched_barrier(0)
; template <class Epi, bool ALIGN_EPI>
; __device__ __forceinline__ void gemm_phase(LAS unsigned char* lds, const int tid, const Gemm g, const StaticOrder& S, const Epi& E) {
;     ...
;             const bool last = (t == nt - 2);
;             const char* a1 = cA + (size_t)(t + 1) * kstepA;
;             const char* a2 = last ? nA : cA + (size_t)(t + 2) * kstepA; const char* b2 = last ? nB : cB + (size_t)(t + 2) * kstepB;
;             const char* a3 = a2 + kstepA; const char* b3 = b2 + kstepB;
;             PG8_LDB(B0, 0, 0); PG8_LDB(B1, 0, 1); PG8_SCHED; PG8_LDA(At, 0, 0); PG8_STAGE(PG8_SA(1, 1), a1 + hstepA, voffA);
;             PG8_WAIT_V(8); PG8_WAIT_L(0); PG8_BAR; PG8_MMA(0, 0, At, B0); PG8_MMA(0, 1, At, B1); PG8_BAR; PG8_SCHED;
;             PG8_LDA(At, 0, 1); PG8_STAGE(PG8_SB(0, 0), b2, voffB); PG8_STAGE(PG8_SB(0, 1), b2 + hstepB, voffB); PG8_STAGE(PG8_SA(0, 0), a2, voffA);
;             PG8_WAIT_V(8); PG8_WAIT_L(0); PG8_BAR; PG8_MMA(1, 0, At, B0); PG8_MMA(1, 1, At, B1); PG8_BAR; PG8_SCHED;
.LBB0_143:
	s_add_u32 s26, s24, 0xfff80080
	s_addc_u32 s27, s25, -1
	s_add_i32 s68, 0, 0x10000
	s_cmp_eq_u32 s67, 28
	s_cselect_b32 s29, s19, s27
	s_cselect_b32 s28, s18, s26
	v_add_u32_e32 v142, s68, v145
	s_cselect_b32 s27, s21, s17
	s_cselect_b32 s26, s20, s15
	s_add_i32 s70, 0, 0x14000
	ds_read_b128 v[148:151], v142
	ds_read_b128 v[152:155], v142 offset:1024
	ds_read_b128 v[156:159], v142 offset:2048
	ds_read_b128 v[160:163], v142 offset:3072
	v_add_u32_e32 v142, s70, v145
	ds_read_b128 v[164:167], v142
	ds_read_b128 v[168:171], v142 offset:1024
	ds_read_b128 v[172:175], v142 offset:2048
	ds_read_b128 v[176:179], v142 offset:3072
	v_lshl_add_u64 v[142:143], s[24:25], 0, v[140:141]
	s_add_i32 m0, s23, 0xc000
	ds_read_b128 v[180:183], v146
	ds_read_b128 v[184:187], v146 offset:1024
	ds_read_b128 v[188:191], v146 offset:2048
	ds_read_b128 v[192:195], v146 offset:3072
	ds_read_b128 v[210:213], v146 offset:4096
	ds_read_b128 v[214:217], v146 offset:5120
	ds_read_b128 v[218:221], v146 offset:6144
	ds_read_b128 v[222:225], v146 offset:7168
	global_load_lds_dwordx4 v[142:143], off
	v_lshl_add_u64 v[142:143], s[24:25], 0, v[138:139]
	s_add_i32 m0, s23, 0xe000
	s_nop 0
	global_load_lds_dwordx4 v[142:143], off
	s_sub_u32 s98, s24, 0x80000
	s_subb_u32 s99, s25, 0
	v_lshl_add_u64 v[142:143], s[98:99], 0, v[140:141]
	s_mov_b32 m0, s56
	s_nop 0
	global_load_lds_dwordx4 v[142:143], off
	v_lshl_add_u64 v[142:143], s[98:99], 0, v[138:139]
	s_mov_b32 m0, s58
	s_nop 0
	global_load_lds_dwordx4 v[142:143], off
	s_nop 0
	s_waitcnt vmcnt(8)
	s_waitcnt lgkmcnt(0)
	s_barrier
	v_mfma_f32_16x16x32_bf16 v[126:129], v[148:151], v[180:183], v[126:129]
	v_mfma_f32_16x16x32_bf16 v[122:125], v[156:159], v[180:183], v[122:125]
	v_mfma_f32_16x16x32_bf16 v[110:113], v[148:151], v[188:191], v[110:113]
	v_mfma_f32_16x16x32_bf16 v[106:109], v[156:159], v[188:191], v[106:109]
	v_mfma_f32_16x16x32_bf16 v[94:97], v[148:151], v[210:213], v[94:97]
	v_mfma_f32_16x16x32_bf16 v[90:93], v[156:159], v[210:213], v[90:93]
	v_mfma_f32_16x16x32_bf16 v[78:81], v[148:151], v[218:221], v[78:81]
	v_mfma_f32_16x16x32_bf16 v[74:77], v[156:159], v[218:221], v[74:77]
	v_mfma_f32_16x16x32_bf16 v[126:129], v[152:155], v[184:187], v[126:129]
	v_mfma_f32_16x16x32_bf16 v[122:125], v[160:163], v[184:187], v[122:125]
	v_mfma_f32_16x16x32_bf16 v[110:113], v[152:155], v[192:195], v[110:113]
	v_mfma_f32_16x16x32_bf16 v[106:109], v[160:163], v[192:195], v[106:109]
	v_mfma_f32_16x16x32_bf16 v[94:97], v[152:155], v[214:217], v[94:97]
	v_mfma_f32_16x16x32_bf16 v[90:93], v[160:163], v[214:217], v[90:93]
	v_mfma_f32_16x16x32_bf16 v[78:81], v[152:155], v[222:225], v[78:81]
	v_mfma_f32_16x16x32_bf16 v[74:77], v[160:163], v[222:225], v[74:77]
	v_mfma_f32_16x16x32_bf16 v[118:121], v[164:167], v[180:183], v[118:121]
	v_mfma_f32_16x16x32_bf16 v[114:117], v[172:175], v[180:183], v[114:117]
	v_mfma_f32_16x16x32_bf16 v[102:105], v[164:167], v[188:191], v[102:105]
	v_mfma_f32_16x16x32_bf16 v[98:101], v[172:175], v[188:191], v[98:101]
	v_mfma_f32_16x16x32_bf16 v[86:89], v[164:167], v[210:213], v[86:89]
	v_mfma_f32_16x16x32_bf16 v[82:85], v[172:175], v[210:213], v[82:85]
	v_mfma_f32_16x16x32_bf16 v[70:73], v[164:167], v[218:221], v[70:73]
	v_mfma_f32_16x16x32_bf16 v[66:69], v[172:175], v[218:221], v[66:69]
	v_mfma_f32_16x16x32_bf16 v[118:121], v[168:171], v[184:187], v[118:121]
	v_mfma_f32_16x16x32_bf16 v[114:117], v[176:179], v[184:187], v[114:117]
	v_mfma_f32_16x16x32_bf16 v[102:105], v[168:171], v[192:195], v[102:105]
	v_mfma_f32_16x16x32_bf16 v[98:101], v[176:179], v[192:195], v[98:101]
	v_mfma_f32_16x16x32_bf16 v[86:89], v[168:171], v[214:217], v[86:89]
	v_mfma_f32_16x16x32_bf16 v[82:85], v[176:179], v[214:217], v[82:85]
	v_mfma_f32_16x16x32_bf16 v[70:73], v[168:171], v[222:225], v[70:73]
	v_mfma_f32_16x16x32_bf16 v[66:69], v[176:179], v[222:225], v[66:69]
	s_barrier
	s_add_i32 s68, s68, s30
	v_lshl_add_u64 v[142:143], s[26:27], 0, v[0:1]
	s_mov_b32 m0, s68
	ds_read_b128 v[180:183], v146 offset:16384
	ds_read_b128 v[184:187], v146 offset:17408
	ds_read_b128 v[188:191], v146 offset:18432
	ds_read_b128 v[192:195], v146 offset:19456
	ds_read_b128 v[210:213], v146 offset:20480
	ds_read_b128 v[214:217], v146 offset:21504
	ds_read_b128 v[218:221], v146 offset:22528
	ds_read_b128 v[222:225], v146 offset:23552
	global_load_lds_dwordx4 v[142:143], off
	s_add_i32 m0, s68, 0x2000
	s_add_u32 s68, s26, 0x80000
	v_lshl_add_u64 v[240:241], s[26:27], 0, v[130:131]
	s_addc_u32 s69, s27, 0
	s_add_i32 s70, s70, s30
	global_load_lds_dwordx4 v[240:241], off
	v_lshl_add_u64 v[242:243], s[68:69], 0, v[0:1]
	s_mov_b32 m0, s70
	v_lshl_add_u64 v[244:245], s[28:29], 0, v[132:133]
	global_load_lds_dwordx4 v[242:243], off
	v_lshl_add_u64 v[242:243], s[68:69], 0, v[130:131]
	s_add_i32 m0, s70, 0x2000
	s_nop 0
	global_load_lds_dwordx4 v[242:243], off
	v_lshl_add_u64 v[242:243], s[28:29], 0, v[134:135]
	s_waitcnt vmcnt(4)
	s_waitcnt lgkmcnt(0)
	s_barrier
; #define PG8_STAGE(bufoff, gbase, voff) do { _Pragma("unroll") for (int _i = 0; _i < 2; ++_i) \
;         __builtin_amdgcn_global_load_lds((const unsigned*)((const char*)(gbase) + (voff)[_i]), (LAS unsigned*)(lds + (bufoff) + ldsw + _i * 8192), 16, 0, 0); } while (0)
; #define PG8_LDA(dst, b, h) do { _Pragma("unroll") for (int m = 0; m < 4; ++m) _Pragma("unroll") for (int k = 0; k < 2; ++k) dst[m][k] = *(const LAS bf16x8*)(lds + PG8_SA(b, h) + aoff + m * 2048 + k * 1024); } while (0)
; #define PG8_LDB(dst, b, h) do { _Pragma("unroll") for (int n = 0; n < 2; ++n) _Pragma("unroll") for (int k = 0; k < 2; ++k) dst[n][k] = *(const LAS bf16x8*)(lds + PG8_SB(b, h) + boff + n * 2048 + k * 1024); } while (0)
; #define PG8_MMA(ai, bj, At, Bt) do { __builtin_amdgcn_s_setprio(1); _Pragma("unroll") for (int m = 0; m < 4; ++m) _Pragma("unroll") for (int n = 0; n < 2; ++n) _Pragma("unroll") for (int k = 0; k < 2; ++k) \
;         acc[ai][bj][m][n] = __builtin_amdgcn_mfma_f32_16x16x32_bf16(Bt[n][k], At[m][k], acc[ai][bj][m][n], 0, 0, 0); __builtin_amdgcn_s_setprio(0); } while (0)
; #define PG8_WAIT_V(n) asm volatile("s_waitcnt vmcnt(" #n ")" ::: "memory")
; #define PG8_WAIT_L(n) asm volatile("s_waitcnt lgkmcnt(" #n ")" ::: "memory")
; #define PG8_BAR __builtin_amdgcn_s_barrier()
; #define PG8_SCHED __builtin_amdgcn_sched_barrier(0)
; template <class Epi, bool ALIGN_EPI>
; __device__ __forceinline__ void gemm_phase(LAS unsigned char* lds, const int tid, const Gemm g, const StaticOrder& S, const Epi& E) {
;     ...
;             PG8_WAIT_V(8); PG8_WAIT_L(0); PG8_BAR; PG8_MMA(1, 0, At, B0); PG8_MMA(1, 1, At, B1); PG8_BAR; PG8_SCHED;
;             PG8_LDB(B0, 1, 0); PG8_LDB(B1, 1, 1); PG8_SCHED; PG8_LDA(At, 1, 0); PG8_STAGE(PG8_SA(0, 1), a2 + hstepA, voffA);
;             PG8_WAIT_V(8); PG8_WAIT_L(0); PG8_BAR; PG8_MMA(0, 0, At, B0); PG8_MMA(0, 1, At, B1); PG8_BAR; PG8_SCHED;
	v_mfma_f32_16x16x32_bf16 v[62:65], v[148:151], v[180:183], v[62:65]
	v_mfma_f32_16x16x32_bf16 v[58:61], v[156:159], v[180:183], v[58:61]
	v_mfma_f32_16x16x32_bf16 v[46:49], v[148:151], v[188:191], v[46:49]
	v_mfma_f32_16x16x32_bf16 v[42:45], v[156:159], v[188:191], v[42:45]
	v_mfma_f32_16x16x32_bf16 v[30:33], v[148:151], v[210:213], v[30:33]
	v_mfma_f32_16x16x32_bf16 v[26:29], v[156:159], v[210:213], v[26:29]
	v_mfma_f32_16x16x32_bf16 v[14:17], v[148:151], v[218:221], v[14:17]
	v_mfma_f32_16x16x32_bf16 v[10:13], v[156:159], v[218:221], v[10:13]
	v_mfma_f32_16x16x32_bf16 v[62:65], v[152:155], v[184:187], v[62:65]
	v_mfma_f32_16x16x32_bf16 v[58:61], v[160:163], v[184:187], v[58:61]
	v_mfma_f32_16x16x32_bf16 v[46:49], v[152:155], v[192:195], v[46:49]
	v_mfma_f32_16x16x32_bf16 v[42:45], v[160:163], v[192:195], v[42:45]
	v_mfma_f32_16x16x32_bf16 v[30:33], v[152:155], v[214:217], v[30:33]
	v_mfma_f32_16x16x32_bf16 v[26:29], v[160:163], v[214:217], v[26:29]
	v_mfma_f32_16x16x32_bf16 v[14:17], v[152:155], v[222:225], v[14:17]
	v_mfma_f32_16x16x32_bf16 v[10:13], v[160:163], v[222:225], v[10:13]
	v_mfma_f32_16x16x32_bf16 v[54:57], v[164:167], v[180:183], v[54:57]
	v_mfma_f32_16x16x32_bf16 v[50:53], v[172:175], v[180:183], v[50:53]
	v_mfma_f32_16x16x32_bf16 v[38:41], v[164:167], v[188:191], v[38:41]
	v_mfma_f32_16x16x32_bf16 v[34:37], v[172:175], v[188:191], v[34:37]
	v_mfma_f32_16x16x32_bf16 v[22:25], v[164:167], v[210:213], v[22:25]
	v_mfma_f32_16x16x32_bf16 v[18:21], v[172:175], v[210:213], v[18:21]
	v_mfma_f32_16x16x32_bf16 v[6:9], v[164:167], v[218:221], v[6:9]
	v_mfma_f32_16x16x32_bf16 v[2:5], v[172:175], v[218:221], v[2:5]
	v_mfma_f32_16x16x32_bf16 v[54:57], v[168:171], v[184:187], v[54:57]
	v_mfma_f32_16x16x32_bf16 v[50:53], v[176:179], v[184:187], v[50:53]
	v_mfma_f32_16x16x32_bf16 v[38:41], v[168:171], v[192:195], v[38:41]
	v_mfma_f32_16x16x32_bf16 v[34:37], v[176:179], v[192:195], v[34:37]
	v_mfma_f32_16x16x32_bf16 v[22:25], v[168:171], v[214:217], v[22:25]
	v_mfma_f32_16x16x32_bf16 v[18:21], v[176:179], v[214:217], v[18:21]
	v_mfma_f32_16x16x32_bf16 v[6:9], v[168:171], v[222:225], v[6:9]
	v_mfma_f32_16x16x32_bf16 v[2:5], v[176:179], v[222:225], v[2:5]
	s_barrier
	s_add_i32 s68, 0, 0x18000
	v_add_u32_e32 v147, s68, v145
	s_add_i32 s69, 0, 0x1c000
	ds_read_b128 v[148:151], v147
	ds_read_b128 v[152:155], v147 offset:1024
	ds_read_b128 v[156:159], v147 offset:2048
	ds_read_b128 v[160:163], v147 offset:3072
	v_add_u32_e32 v147, s69, v145
	ds_read_b128 v[164:167], v147
	ds_read_b128 v[168:171], v147 offset:1024
	ds_read_b128 v[172:175], v147 offset:2048
	ds_read_b128 v[176:179], v147 offset:3072
	s_mov_b32 m0, s23
	s_nop 0
	global_load_lds_dwordx4 v[242:243], off
	s_mov_b32 m0, s52
	s_nop 0
	global_load_lds_dwordx4 v[244:245], off
	s_add_u32 s28, s28, 0x80000
	s_addc_u32 s29, s29, 0
	s_mov_b32 m0, s54
	v_lshl_add_u64 v[246:247], s[28:29], 0, v[134:135]
	ds_read_b128 v[180:183], v146 offset:32768
	ds_read_b128 v[184:187], v146 offset:33792
	ds_read_b128 v[188:191], v146 offset:34816
	ds_read_b128 v[192:195], v146 offset:35840
	ds_read_b128 v[210:213], v146 offset:36864
	ds_read_b128 v[214:217], v146 offset:37888
	ds_read_b128 v[218:221], v146 offset:38912
	ds_read_b128 v[222:225], v146 offset:39936
	global_load_lds_dwordx4 v[246:247], off
	v_lshl_add_u64 v[246:247], s[28:29], 0, v[132:133]
	s_mov_b32 m0, s55
	s_nop 0
	global_load_lds_dwordx4 v[246:247], off
	s_waitcnt vmcnt(8)
	s_waitcnt lgkmcnt(0)
	s_barrier
; #define PG8_STAGE(bufoff, gbase, voff) do { _Pragma("unroll") for (int _i = 0; _i < 2; ++_i) \
;         __builtin_amdgcn_global_load_lds((const unsigned*)((const char*)(gbase) + (voff)[_i]), (LAS unsigned*)(lds + (bufoff) + ldsw + _i * 8192), 16, 0, 0); } while (0)
; #define PG8_LDA(dst, b, h) do { _Pragma("unroll") for (int m = 0; m < 4; ++m) _Pragma("unroll") for (int k = 0; k < 2; ++k) dst[m][k] = *(const LAS bf16x8*)(lds + PG8_SA(b, h) + aoff + m * 2048 + k * 1024); } while (0)
; #define PG8_MMA(ai, bj, At, Bt) do { __builtin_amdgcn_s_setprio(1); _Pragma("unroll") for (int m = 0; m < 4; ++m) _Pragma("unroll") for (int n = 0; n < 2; ++n) _Pragma("unroll") for (int k = 0; k < 2; ++k) \
;         acc[ai][bj][m][n] = __builtin_amdgcn_mfma_f32_16x16x32_bf16(Bt[n][k], At[m][k], acc[ai][bj][m][n], 0, 0, 0); __builtin_amdgcn_s_setprio(0); } while (0)
; #define PG8_WAIT_V(n) asm volatile("s_waitcnt vmcnt(" #n ")" ::: "memory")
; #define PG8_WAIT_L(n) asm volatile("s_waitcnt lgkmcnt(" #n ")" ::: "memory")
; #define PG8_BAR __builtin_amdgcn_s_barrier()
; #define PG8_SCHED __builtin_amdgcn_sched_barrier(0)
; template <class Epi, bool ALIGN_EPI>
; __device__ __forceinline__ void gemm_phase(LAS unsigned char* lds, const int tid, const Gemm g, const StaticOrder& S, const Epi& E) {
;     ...
;             PG8_WAIT_V(8); PG8_WAIT_L(0); PG8_BAR; PG8_MMA(0, 0, At, B0); PG8_MMA(0, 1, At, B1); PG8_BAR; PG8_SCHED;
;             PG8_LDA(At, 1, 1); PG8_STAGE(PG8_SB(1, 0), b3, voffB); PG8_STAGE(PG8_SB(1, 1), b3 + hstepB, voffB); PG8_STAGE(PG8_SA(1, 0), a3, voffA);
;             PG8_WAIT_V(8); PG8_WAIT_L(0); PG8_BAR; PG8_MMA(1, 0, At, B0); PG8_MMA(1, 1, At, B1); PG8_BAR; PG8_SCHED;
;         }
;         if constexpr (ALIGN_EPI) { if (wr == 0) PG8_BAR; }
	v_mfma_f32_16x16x32_bf16 v[126:129], v[148:151], v[180:183], v[126:129]
	v_mfma_f32_16x16x32_bf16 v[122:125], v[156:159], v[180:183], v[122:125]
	v_mfma_f32_16x16x32_bf16 v[110:113], v[148:151], v[188:191], v[110:113]
	v_mfma_f32_16x16x32_bf16 v[106:109], v[156:159], v[188:191], v[106:109]
	v_mfma_f32_16x16x32_bf16 v[94:97], v[148:151], v[210:213], v[94:97]
	v_mfma_f32_16x16x32_bf16 v[90:93], v[156:159], v[210:213], v[90:93]
	v_mfma_f32_16x16x32_bf16 v[78:81], v[148:151], v[218:221], v[78:81]
	v_mfma_f32_16x16x32_bf16 v[74:77], v[156:159], v[218:221], v[74:77]
	v_mfma_f32_16x16x32_bf16 v[126:129], v[152:155], v[184:187], v[126:129]
	v_mfma_f32_16x16x32_bf16 v[122:125], v[160:163], v[184:187], v[122:125]
	v_mfma_f32_16x16x32_bf16 v[110:113], v[152:155], v[192:195], v[110:113]
	v_mfma_f32_16x16x32_bf16 v[106:109], v[160:163], v[192:195], v[106:109]
	v_mfma_f32_16x16x32_bf16 v[94:97], v[152:155], v[214:217], v[94:97]
	v_mfma_f32_16x16x32_bf16 v[90:93], v[160:163], v[214:217], v[90:93]
	v_mfma_f32_16x16x32_bf16 v[78:81], v[152:155], v[222:225], v[78:81]
	v_mfma_f32_16x16x32_bf16 v[74:77], v[160:163], v[222:225], v[74:77]
	v_mfma_f32_16x16x32_bf16 v[118:121], v[164:167], v[180:183], v[118:121]
	v_mfma_f32_16x16x32_bf16 v[114:117], v[172:175], v[180:183], v[114:117]
	v_mfma_f32_16x16x32_bf16 v[102:105], v[164:167], v[188:191], v[102:105]
	v_mfma_f32_16x16x32_bf16 v[98:101], v[172:175], v[188:191], v[98:101]
	v_mfma_f32_16x16x32_bf16 v[86:89], v[164:167], v[210:213], v[86:89]
	v_mfma_f32_16x16x32_bf16 v[82:85], v[172:175], v[210:213], v[82:85]
	v_mfma_f32_16x16x32_bf16 v[70:73], v[164:167], v[218:221], v[70:73]
	v_mfma_f32_16x16x32_bf16 v[66:69], v[172:175], v[218:221], v[66:69]
	v_mfma_f32_16x16x32_bf16 v[118:121], v[168:171], v[184:187], v[118:121]
	v_mfma_f32_16x16x32_bf16 v[114:117], v[176:179], v[184:187], v[114:117]
	v_mfma_f32_16x16x32_bf16 v[102:105], v[168:171], v[192:195], v[102:105]
	v_mfma_f32_16x16x32_bf16 v[98:101], v[176:179], v[192:195], v[98:101]
	v_mfma_f32_16x16x32_bf16 v[86:89], v[168:171], v[214:217], v[86:89]
	v_mfma_f32_16x16x32_bf16 v[82:85], v[176:179], v[214:217], v[82:85]
	v_mfma_f32_16x16x32_bf16 v[70:73], v[168:171], v[222:225], v[70:73]
	v_mfma_f32_16x16x32_bf16 v[66:69], v[176:179], v[222:225], v[66:69]
	s_barrier
	s_add_i32 s28, s68, s30
	v_lshl_add_u64 v[142:143], v[142:143], 0, s[42:43]
	s_mov_b32 m0, s28
	ds_read_b128 v[180:183], v146 offset:49152
	ds_read_b128 v[184:187], v146 offset:50176
	ds_read_b128 v[188:191], v146 offset:51200
	ds_read_b128 v[192:195], v146 offset:52224
	ds_read_b128 v[210:213], v146 offset:53248
	ds_read_b128 v[214:217], v146 offset:54272
	ds_read_b128 v[218:221], v146 offset:55296
	ds_read_b128 v[222:225], v146 offset:56320
	global_load_lds_dwordx4 v[142:143], off
	s_add_i32 m0, s28, 0x2000
	s_add_u32 s26, s26, 0x80080
	v_lshl_add_u64 v[142:143], v[240:241], 0, s[42:43]
	s_addc_u32 s27, s27, 0
	s_add_i32 s28, s69, s30
	global_load_lds_dwordx4 v[142:143], off
	v_lshl_add_u64 v[142:143], s[26:27], 0, v[0:1]
	s_mov_b32 m0, s28
	s_nop 0
	global_load_lds_dwordx4 v[142:143], off
	v_lshl_add_u64 v[142:143], s[26:27], 0, v[130:131]
	s_add_i32 m0, s28, 0x2000
	s_nop 0
	global_load_lds_dwordx4 v[142:143], off
	s_nop 0
	s_waitcnt vmcnt(4)
	s_waitcnt lgkmcnt(0)
	s_barrier
	v_mfma_f32_16x16x32_bf16 v[62:65], v[148:151], v[180:183], v[62:65]
	v_mfma_f32_16x16x32_bf16 v[58:61], v[156:159], v[180:183], v[58:61]
	v_mfma_f32_16x16x32_bf16 v[46:49], v[148:151], v[188:191], v[46:49]
	v_mfma_f32_16x16x32_bf16 v[42:45], v[156:159], v[188:191], v[42:45]
	v_mfma_f32_16x16x32_bf16 v[30:33], v[148:151], v[210:213], v[30:33]
	v_mfma_f32_16x16x32_bf16 v[26:29], v[156:159], v[210:213], v[26:29]
	v_mfma_f32_16x16x32_bf16 v[14:17], v[148:151], v[218:221], v[14:17]
	v_mfma_f32_16x16x32_bf16 v[10:13], v[156:159], v[218:221], v[10:13]
	v_mfma_f32_16x16x32_bf16 v[62:65], v[152:155], v[184:187], v[62:65]
	v_mfma_f32_16x16x32_bf16 v[58:61], v[160:163], v[184:187], v[58:61]
	v_mfma_f32_16x16x32_bf16 v[46:49], v[152:155], v[192:195], v[46:49]
	v_mfma_f32_16x16x32_bf16 v[42:45], v[160:163], v[192:195], v[42:45]
	v_mfma_f32_16x16x32_bf16 v[30:33], v[152:155], v[214:217], v[30:33]
	v_mfma_f32_16x16x32_bf16 v[26:29], v[160:163], v[214:217], v[26:29]
	v_mfma_f32_16x16x32_bf16 v[14:17], v[152:155], v[222:225], v[14:17]
	v_mfma_f32_16x16x32_bf16 v[10:13], v[160:163], v[222:225], v[10:13]
	v_mfma_f32_16x16x32_bf16 v[54:57], v[164:167], v[180:183], v[54:57]
	v_mfma_f32_16x16x32_bf16 v[50:53], v[172:175], v[180:183], v[50:53]
	v_mfma_f32_16x16x32_bf16 v[38:41], v[164:167], v[188:191], v[38:41]
	v_mfma_f32_16x16x32_bf16 v[34:37], v[172:175], v[188:191], v[34:37]
	v_mfma_f32_16x16x32_bf16 v[22:25], v[164:167], v[210:213], v[22:25]
	v_mfma_f32_16x16x32_bf16 v[18:21], v[172:175], v[210:213], v[18:21]
	v_mfma_f32_16x16x32_bf16 v[6:9], v[164:167], v[218:221], v[6:9]
	v_mfma_f32_16x16x32_bf16 v[2:5], v[172:175], v[218:221], v[2:5]
	v_mfma_f32_16x16x32_bf16 v[54:57], v[168:171], v[184:187], v[54:57]
	v_mfma_f32_16x16x32_bf16 v[50:53], v[176:179], v[184:187], v[50:53]
	v_mfma_f32_16x16x32_bf16 v[38:41], v[168:171], v[192:195], v[38:41]
	v_mfma_f32_16x16x32_bf16 v[34:37], v[176:179], v[192:195], v[34:37]
	v_mfma_f32_16x16x32_bf16 v[22:25], v[168:171], v[214:217], v[22:25]
	v_mfma_f32_16x16x32_bf16 v[18:21], v[176:179], v[214:217], v[18:21]
	v_mfma_f32_16x16x32_bf16 v[6:9], v[168:171], v[222:225], v[6:9]
	v_mfma_f32_16x16x32_bf16 v[2:5], v[176:179], v[222:225], v[2:5]
	s_barrier
	s_add_i32 s67, s67, 2
	s_add_u32 s15, s15, 0x100
	s_addc_u32 s17, s17, 0
	s_add_u32 s24, s24, 0x100
	s_addc_u32 s25, s25, 0
	s_cmp_gt_u32 s67, 29
	s_cbranch_scc0 .LBB0_143
	s_and_b64 vcc, exec, s[12:13]
	s_cbranch_vccz .LBB0_146
	s_barrier

; #define PG8_STAGE(bufoff, gbase, voff) do { _Pragma("unroll") for (int _i = 0; _i < 2; ++_i) \
;         __builtin_amdgcn_global_load_lds((const unsigned*)((const char*)(gbase) + (voff)[_i]), (LAS unsigned*)(lds + (bufoff) + ldsw + _i * 8192), 16, 0, 0); } while (0)
; #define PG8_LDA(dst, b, h) do { _Pragma("unroll") for (int m = 0; m < 4; ++m) _Pragma("unroll") for (int k = 0; k < 2; ++k) dst[m][k] = *(const LAS bf16x8*)(lds + PG8_SA(b, h) + aoff + m * 2048 + k * 1024); } while (0)
; #define PG8_LDB(dst, b, h) do { _Pragma("unroll") for (int n = 0; n < 2; ++n) _Pragma("unroll") for (int k = 0; k < 2; ++k) dst[n][k] = *(const LAS bf16x8*)(lds + PG8_SB(b, h) + boff + n * 2048 + k * 1024); } while (0)
; #define PG8_MMA(ai, bj, At, Bt) do { __builtin_amdgcn_s_setprio(1); _Pragma("unroll") for (int m = 0; m < 4; ++m) _Pragma("unroll") for (int n = 0; n < 2; ++n) _Pragma("unroll") for (int k = 0; k < 2; ++k) \
;         acc[ai][bj][m][n] = __builtin_amdgcn_mfma_f32_16x16x32_bf16(Bt[n][k], At[m][k], acc[ai][bj][m][n], 0, 0, 0); __builtin_amdgcn_s_setprio(0); } while (0)
; #define PG8_WAIT_V(n) asm volatile("s_waitcnt vmcnt(" #n ")" ::: "memory")
; #define PG8_WAIT_L(n) asm volatile("s_waitcnt lgkmcnt(" #n ")" ::: "memory")
; #define PG8_BAR __builtin_amdgcn_s_barrier()
; #define PG8_SCHED __builtin_amdgcn_sched_barrier(0)
; template <class Epi, bool ALIGN_EPI>
; __device__ __forceinline__ void gemm_phase(LAS unsigned char* lds, const int tid, const Gemm g, const StaticOrder& S, const Epi& E) {
;     ...
;             const bool last = (t == nt - 2);
;             const char* a1 = cA + (size_t)(t + 1) * kstepA;
;             const char* a2 = last ? nA : cA + (size_t)(t + 2) * kstepA; const char* b2 = last ? nB : cB + (size_t)(t + 2) * kstepB;
;             const char* a3 = a2 + kstepA; const char* b3 = b2 + kstepB;
;             PG8_LDB(B0, 0, 0); PG8_LDB(B1, 0, 1); PG8_SCHED; PG8_LDA(At, 0, 0); PG8_STAGE(PG8_SA(1, 1), a1 + hstepA, voffA);
;             PG8_WAIT_V(8); PG8_WAIT_L(0); PG8_BAR; PG8_MMA(0, 0, At, B0); PG8_MMA(0, 1, At, B1); PG8_BAR; PG8_SCHED;
;             PG8_LDA(At, 0, 1); PG8_STAGE(PG8_SB(0, 0), b2, voffB); PG8_STAGE(PG8_SB(0, 1), b2 + hstepB, voffB); PG8_STAGE(PG8_SA(0, 0), a2, voffA);
;             PG8_WAIT_V(8); PG8_WAIT_L(0); PG8_BAR; PG8_MMA(1, 0, At, B0); PG8_MMA(1, 1, At, B1); PG8_BAR; PG8_SCHED;
.LBB0_209:
	s_add_i32 s72, s34, 2
	s_add_u32 s35, s30, 0xfff80080
	s_addc_u32 s54, s31, -1
	s_cmp_eq_u32 s21, s34
	s_cselect_b32 s55, s23, s54
	s_cselect_b32 s54, s22, s35
	s_cselect_b32 s35, s25, s71
	s_cselect_b32 s34, s24, s27
	s_add_i32 s73, 0, 0x10000
	s_add_i32 s85, 0, 0x14000
	v_add_u32_e32 v148, s73, v175
	v_add_u32_e32 v164, s85, v175
	ds_read_b128 v[136:139], v148
	ds_read_b128 v[140:143], v148 offset:1024
	ds_read_b128 v[144:147], v148 offset:2048
	ds_read_b128 v[148:151], v148 offset:3072
	ds_read_b128 v[152:155], v164
	ds_read_b128 v[156:159], v164 offset:1024
	ds_read_b128 v[160:163], v164 offset:2048
	ds_read_b128 v[164:167], v164 offset:3072
	v_lshl_add_u64 v[172:173], s[30:31], 0, v[134:135]
	s_add_i32 m0, s58, 0xc000
	ds_read_b128 v[168:171], v177
	ds_read_b128 v[178:181], v177 offset:1024
	ds_read_b128 v[182:185], v177 offset:2048
	ds_read_b128 v[186:189], v177 offset:3072
	ds_read_b128 v[190:193], v177 offset:4096
	ds_read_b128 v[210:213], v177 offset:5120
	ds_read_b128 v[214:217], v177 offset:6144
	ds_read_b128 v[218:221], v177 offset:7168
	global_load_lds_dwordx4 v[172:173], off
	v_lshl_add_u64 v[172:173], s[30:31], 0, v[132:133]
	s_add_i32 m0, s58, 0xe000
	s_nop 0
	global_load_lds_dwordx4 v[172:173], off
	s_sub_u32 s98, s30, 0x80000
	s_subb_u32 s99, s31, 0
	v_lshl_add_u64 v[172:173], s[98:99], 0, v[134:135]
	s_mov_b32 m0, s65
	s_nop 0
	global_load_lds_dwordx4 v[172:173], off
	v_lshl_add_u64 v[172:173], s[98:99], 0, v[132:133]
	s_mov_b32 m0, s66
	s_nop 0
	global_load_lds_dwordx4 v[172:173], off
	s_nop 0
	s_waitcnt vmcnt(8)
	s_waitcnt lgkmcnt(0)
	s_barrier
	v_mfma_f32_16x16x32_bf16 v[126:129], v[136:139], v[168:171], v[126:129]
	v_mfma_f32_16x16x32_bf16 v[94:97], v[144:147], v[168:171], v[94:97]
	v_mfma_f32_16x16x32_bf16 v[122:125], v[136:139], v[182:185], v[122:125]
	v_mfma_f32_16x16x32_bf16 v[90:93], v[144:147], v[182:185], v[90:93]
	v_mfma_f32_16x16x32_bf16 v[118:121], v[136:139], v[190:193], v[118:121]
	v_mfma_f32_16x16x32_bf16 v[86:89], v[144:147], v[190:193], v[86:89]
	v_mfma_f32_16x16x32_bf16 v[114:117], v[136:139], v[214:217], v[114:117]
	v_mfma_f32_16x16x32_bf16 v[82:85], v[144:147], v[214:217], v[82:85]
	v_mfma_f32_16x16x32_bf16 v[126:129], v[140:143], v[178:181], v[126:129]
	v_mfma_f32_16x16x32_bf16 v[94:97], v[148:151], v[178:181], v[94:97]
	v_mfma_f32_16x16x32_bf16 v[122:125], v[140:143], v[186:189], v[122:125]
	v_mfma_f32_16x16x32_bf16 v[90:93], v[148:151], v[186:189], v[90:93]
	v_mfma_f32_16x16x32_bf16 v[118:121], v[140:143], v[210:213], v[118:121]
	v_mfma_f32_16x16x32_bf16 v[86:89], v[148:151], v[210:213], v[86:89]
	v_mfma_f32_16x16x32_bf16 v[114:117], v[140:143], v[218:221], v[114:117]
	v_mfma_f32_16x16x32_bf16 v[82:85], v[148:151], v[218:221], v[82:85]
	v_mfma_f32_16x16x32_bf16 v[62:65], v[152:155], v[168:171], v[62:65]
	v_mfma_f32_16x16x32_bf16 v[42:45], v[160:163], v[168:171], v[42:45]
	v_mfma_f32_16x16x32_bf16 v[58:61], v[152:155], v[182:185], v[58:61]
	v_mfma_f32_16x16x32_bf16 v[34:37], v[160:163], v[182:185], v[34:37]
	v_mfma_f32_16x16x32_bf16 v[54:57], v[152:155], v[190:193], v[54:57]
	v_mfma_f32_16x16x32_bf16 v[26:29], v[160:163], v[190:193], v[26:29]
	v_mfma_f32_16x16x32_bf16 v[50:53], v[152:155], v[214:217], v[50:53]
	v_mfma_f32_16x16x32_bf16 v[18:21], v[160:163], v[214:217], v[18:21]
	v_mfma_f32_16x16x32_bf16 v[62:65], v[156:159], v[178:181], v[62:65]
	v_mfma_f32_16x16x32_bf16 v[42:45], v[164:167], v[178:181], v[42:45]
	v_mfma_f32_16x16x32_bf16 v[58:61], v[156:159], v[186:189], v[58:61]
	v_mfma_f32_16x16x32_bf16 v[34:37], v[164:167], v[186:189], v[34:37]
	v_mfma_f32_16x16x32_bf16 v[54:57], v[156:159], v[210:213], v[54:57]
	v_mfma_f32_16x16x32_bf16 v[26:29], v[164:167], v[210:213], v[26:29]
	v_mfma_f32_16x16x32_bf16 v[50:53], v[156:159], v[218:221], v[50:53]
	v_mfma_f32_16x16x32_bf16 v[18:21], v[164:167], v[218:221], v[18:21]
	s_barrier
	s_add_i32 s73, s73, s56
	v_lshl_add_u64 v[172:173], s[34:35], 0, v[0:1]
	s_mov_b32 m0, s73
	ds_read_b128 v[168:171], v177 offset:16384
	ds_read_b128 v[178:181], v177 offset:17408
	ds_read_b128 v[182:185], v177 offset:18432
	ds_read_b128 v[186:189], v177 offset:19456
	ds_read_b128 v[190:193], v177 offset:20480
	ds_read_b128 v[210:213], v177 offset:21504
	ds_read_b128 v[214:217], v177 offset:22528
	ds_read_b128 v[218:221], v177 offset:23552
	global_load_lds_dwordx4 v[172:173], off
	s_add_i32 m0, s73, 0x2000
	s_add_u32 s90, s34, 0x80000
	v_lshl_add_u64 v[194:195], s[34:35], 0, v[130:131]
	s_addc_u32 s91, s35, 0
	s_add_i32 s73, s85, s56
	global_load_lds_dwordx4 v[194:195], off
	v_lshl_add_u64 v[222:223], s[90:91], 0, v[0:1]
	s_mov_b32 m0, s73
	v_lshl_add_u64 v[224:225], s[54:55], 0, v[130:131]
	global_load_lds_dwordx4 v[222:223], off
	v_lshl_add_u64 v[222:223], s[90:91], 0, v[130:131]
	s_add_i32 m0, s73, 0x2000
	s_nop 0
	global_load_lds_dwordx4 v[222:223], off
	v_lshl_add_u64 v[222:223], s[54:55], 0, v[0:1]
	s_waitcnt vmcnt(4)
	s_waitcnt lgkmcnt(0)
	s_barrier
; #define PG8_STAGE(bufoff, gbase, voff) do { _Pragma("unroll") for (int _i = 0; _i < 2; ++_i) \
;         __builtin_amdgcn_global_load_lds((const unsigned*)((const char*)(gbase) + (voff)[_i]), (LAS unsigned*)(lds + (bufoff) + ldsw + _i * 8192), 16, 0, 0); } while (0)
; #define PG8_LDA(dst, b, h) do { _Pragma("unroll") for (int m = 0; m < 4; ++m) _Pragma("unroll") for (int k = 0; k < 2; ++k) dst[m][k] = *(const LAS bf16x8*)(lds + PG8_SA(b, h) + aoff + m * 2048 + k * 1024); } while (0)
; #define PG8_LDB(dst, b, h) do { _Pragma("unroll") for (int n = 0; n < 2; ++n) _Pragma("unroll") for (int k = 0; k < 2; ++k) dst[n][k] = *(const LAS bf16x8*)(lds + PG8_SB(b, h) + boff + n * 2048 + k * 1024); } while (0)
; #define PG8_MMA(ai, bj, At, Bt) do { __builtin_amdgcn_s_setprio(1); _Pragma("unroll") for (int m = 0; m < 4; ++m) _Pragma("unroll") for (int n = 0; n < 2; ++n) _Pragma("unroll") for (int k = 0; k < 2; ++k) \
;         acc[ai][bj][m][n] = __builtin_amdgcn_mfma_f32_16x16x32_bf16(Bt[n][k], At[m][k], acc[ai][bj][m][n], 0, 0, 0); __builtin_amdgcn_s_setprio(0); } while (0)
; #define PG8_WAIT_V(n) asm volatile("s_waitcnt vmcnt(" #n ")" ::: "memory")
; #define PG8_WAIT_L(n) asm volatile("s_waitcnt lgkmcnt(" #n ")" ::: "memory")
; #define PG8_BAR __builtin_amdgcn_s_barrier()
; #define PG8_SCHED __builtin_amdgcn_sched_barrier(0)
; template <class Epi, bool ALIGN_EPI>
; __device__ __forceinline__ void gemm_phase(LAS unsigned char* lds, const int tid, const Gemm g, const StaticOrder& S, const Epi& E) {
;     ...
;             PG8_WAIT_V(8); PG8_WAIT_L(0); PG8_BAR; PG8_MMA(1, 0, At, B0); PG8_MMA(1, 1, At, B1); PG8_BAR; PG8_SCHED;
;             PG8_LDB(B0, 1, 0); PG8_LDB(B1, 1, 1); PG8_SCHED; PG8_LDA(At, 1, 0); PG8_STAGE(PG8_SA(0, 1), a2 + hstepA, voffA);
;             PG8_WAIT_V(8); PG8_WAIT_L(0); PG8_BAR; PG8_MMA(0, 0, At, B0); PG8_MMA(0, 1, At, B1); PG8_BAR; PG8_SCHED;
	v_mfma_f32_16x16x32_bf16 v[110:113], v[136:139], v[168:171], v[110:113]
	v_mfma_f32_16x16x32_bf16 v[78:81], v[144:147], v[168:171], v[78:81]
	v_mfma_f32_16x16x32_bf16 v[106:109], v[136:139], v[182:185], v[106:109]
	v_mfma_f32_16x16x32_bf16 v[74:77], v[144:147], v[182:185], v[74:77]
	v_mfma_f32_16x16x32_bf16 v[102:105], v[136:139], v[190:193], v[102:105]
	v_mfma_f32_16x16x32_bf16 v[70:73], v[144:147], v[190:193], v[70:73]
	v_mfma_f32_16x16x32_bf16 v[98:101], v[136:139], v[214:217], v[98:101]
	v_mfma_f32_16x16x32_bf16 v[66:69], v[144:147], v[214:217], v[66:69]
	v_mfma_f32_16x16x32_bf16 v[110:113], v[140:143], v[178:181], v[110:113]
	v_mfma_f32_16x16x32_bf16 v[78:81], v[148:151], v[178:181], v[78:81]
	v_mfma_f32_16x16x32_bf16 v[106:109], v[140:143], v[186:189], v[106:109]
	v_mfma_f32_16x16x32_bf16 v[74:77], v[148:151], v[186:189], v[74:77]
	v_mfma_f32_16x16x32_bf16 v[102:105], v[140:143], v[210:213], v[102:105]
	v_mfma_f32_16x16x32_bf16 v[70:73], v[148:151], v[210:213], v[70:73]
	v_mfma_f32_16x16x32_bf16 v[98:101], v[140:143], v[218:221], v[98:101]
	v_mfma_f32_16x16x32_bf16 v[66:69], v[148:151], v[218:221], v[66:69]
	v_mfma_f32_16x16x32_bf16 v[46:49], v[152:155], v[168:171], v[46:49]
	v_mfma_f32_16x16x32_bf16 v[14:17], v[160:163], v[168:171], v[14:17]
	v_mfma_f32_16x16x32_bf16 v[38:41], v[152:155], v[182:185], v[38:41]
	v_mfma_f32_16x16x32_bf16 v[10:13], v[160:163], v[182:185], v[10:13]
	v_mfma_f32_16x16x32_bf16 v[30:33], v[152:155], v[190:193], v[30:33]
	v_mfma_f32_16x16x32_bf16 v[6:9], v[160:163], v[190:193], v[6:9]
	v_mfma_f32_16x16x32_bf16 v[22:25], v[152:155], v[214:217], v[22:25]
	v_mfma_f32_16x16x32_bf16 v[2:5], v[160:163], v[214:217], v[2:5]
	v_mfma_f32_16x16x32_bf16 v[46:49], v[156:159], v[178:181], v[46:49]
	v_mfma_f32_16x16x32_bf16 v[14:17], v[164:167], v[178:181], v[14:17]
	v_mfma_f32_16x16x32_bf16 v[38:41], v[156:159], v[186:189], v[38:41]
	v_mfma_f32_16x16x32_bf16 v[10:13], v[164:167], v[186:189], v[10:13]
	v_mfma_f32_16x16x32_bf16 v[30:33], v[156:159], v[210:213], v[30:33]
	v_mfma_f32_16x16x32_bf16 v[6:9], v[164:167], v[210:213], v[6:9]
	v_mfma_f32_16x16x32_bf16 v[22:25], v[156:159], v[218:221], v[22:25]
	v_mfma_f32_16x16x32_bf16 v[2:5], v[164:167], v[218:221], v[2:5]
	s_barrier
	s_add_i32 s73, 0, 0x18000
	s_add_i32 s85, 0, 0x1c000
	v_add_u32_e32 v148, s73, v175
	v_add_u32_e32 v164, s85, v175
	ds_read_b128 v[136:139], v148
	ds_read_b128 v[140:143], v148 offset:1024
	ds_read_b128 v[144:147], v148 offset:2048
	ds_read_b128 v[148:151], v148 offset:3072
	ds_read_b128 v[152:155], v164
	ds_read_b128 v[156:159], v164 offset:1024
	ds_read_b128 v[160:163], v164 offset:2048
	ds_read_b128 v[164:167], v164 offset:3072
	s_mov_b32 m0, s58
	s_nop 0
	global_load_lds_dwordx4 v[222:223], off
	s_mov_b32 m0, s60
	s_nop 0
	global_load_lds_dwordx4 v[224:225], off
	s_add_u32 s54, s54, 0x80000
	s_addc_u32 s55, s55, 0
	s_mov_b32 m0, s61
	v_lshl_add_u64 v[240:241], s[54:55], 0, v[0:1]
	ds_read_b128 v[168:171], v177 offset:32768
	ds_read_b128 v[178:181], v177 offset:33792
	ds_read_b128 v[182:185], v177 offset:34816
	ds_read_b128 v[186:189], v177 offset:35840
	ds_read_b128 v[190:193], v177 offset:36864
	ds_read_b128 v[210:213], v177 offset:37888
	ds_read_b128 v[214:217], v177 offset:38912
	ds_read_b128 v[218:221], v177 offset:39936
	global_load_lds_dwordx4 v[240:241], off
	v_lshl_add_u64 v[240:241], s[54:55], 0, v[130:131]
	s_mov_b32 m0, s62
	s_nop 0
	global_load_lds_dwordx4 v[240:241], off
	s_waitcnt vmcnt(8)
	s_waitcnt lgkmcnt(0)
	s_barrier
; #define PG8_STAGE(bufoff, gbase, voff) do { _Pragma("unroll") for (int _i = 0; _i < 2; ++_i) \
;         __builtin_amdgcn_global_load_lds((const unsigned*)((const char*)(gbase) + (voff)[_i]), (LAS unsigned*)(lds + (bufoff) + ldsw + _i * 8192), 16, 0, 0); } while (0)
; #define PG8_LDA(dst, b, h) do { _Pragma("unroll") for (int m = 0; m < 4; ++m) _Pragma("unroll") for (int k = 0; k < 2; ++k) dst[m][k] = *(const LAS bf16x8*)(lds + PG8_SA(b, h) + aoff + m * 2048 + k * 1024); } while (0)
; #define PG8_MMA(ai, bj, At, Bt) do { __builtin_amdgcn_s_setprio(1); _Pragma("unroll") for (int m = 0; m < 4; ++m) _Pragma("unroll") for (int n = 0; n < 2; ++n) _Pragma("unroll") for (int k = 0; k < 2; ++k) \
;         acc[ai][bj][m][n] = __builtin_amdgcn_mfma_f32_16x16x32_bf16(Bt[n][k], At[m][k], acc[ai][bj][m][n], 0, 0, 0); __builtin_amdgcn_s_setprio(0); } while (0)
; #define PG8_WAIT_V(n) asm volatile("s_waitcnt vmcnt(" #n ")" ::: "memory")
; #define PG8_WAIT_L(n) asm volatile("s_waitcnt lgkmcnt(" #n ")" ::: "memory")
; #define PG8_BAR __builtin_amdgcn_s_barrier()
; #define PG8_SCHED __builtin_amdgcn_sched_barrier(0)
; template <class Epi, bool ALIGN_EPI>
; __device__ __forceinline__ void gemm_phase(LAS unsigned char* lds, const int tid, const Gemm g, const StaticOrder& S, const Epi& E) {
;     ...
;             PG8_WAIT_V(8); PG8_WAIT_L(0); PG8_BAR; PG8_MMA(0, 0, At, B0); PG8_MMA(0, 1, At, B1); PG8_BAR; PG8_SCHED;
;             PG8_LDA(At, 1, 1); PG8_STAGE(PG8_SB(1, 0), b3, voffB); PG8_STAGE(PG8_SB(1, 1), b3 + hstepB, voffB); PG8_STAGE(PG8_SA(1, 0), a3, voffA);
;             PG8_WAIT_V(8); PG8_WAIT_L(0); PG8_BAR; PG8_MMA(1, 0, At, B0); PG8_MMA(1, 1, At, B1); PG8_BAR; PG8_SCHED;
;         }
;         if constexpr (ALIGN_EPI) { if (wr == 0) PG8_BAR; }
	v_mfma_f32_16x16x32_bf16 v[126:129], v[136:139], v[168:171], v[126:129]
	v_mfma_f32_16x16x32_bf16 v[94:97], v[144:147], v[168:171], v[94:97]
	v_mfma_f32_16x16x32_bf16 v[122:125], v[136:139], v[182:185], v[122:125]
	v_mfma_f32_16x16x32_bf16 v[90:93], v[144:147], v[182:185], v[90:93]
	v_mfma_f32_16x16x32_bf16 v[118:121], v[136:139], v[190:193], v[118:121]
	v_mfma_f32_16x16x32_bf16 v[86:89], v[144:147], v[190:193], v[86:89]
	v_mfma_f32_16x16x32_bf16 v[114:117], v[136:139], v[214:217], v[114:117]
	v_mfma_f32_16x16x32_bf16 v[82:85], v[144:147], v[214:217], v[82:85]
	v_mfma_f32_16x16x32_bf16 v[126:129], v[140:143], v[178:181], v[126:129]
	v_mfma_f32_16x16x32_bf16 v[94:97], v[148:151], v[178:181], v[94:97]
	v_mfma_f32_16x16x32_bf16 v[122:125], v[140:143], v[186:189], v[122:125]
	v_mfma_f32_16x16x32_bf16 v[90:93], v[148:151], v[186:189], v[90:93]
	v_mfma_f32_16x16x32_bf16 v[118:121], v[140:143], v[210:213], v[118:121]
	v_mfma_f32_16x16x32_bf16 v[86:89], v[148:151], v[210:213], v[86:89]
	v_mfma_f32_16x16x32_bf16 v[114:117], v[140:143], v[218:221], v[114:117]
	v_mfma_f32_16x16x32_bf16 v[82:85], v[148:151], v[218:221], v[82:85]
	v_mfma_f32_16x16x32_bf16 v[62:65], v[152:155], v[168:171], v[62:65]
	v_mfma_f32_16x16x32_bf16 v[42:45], v[160:163], v[168:171], v[42:45]
	v_mfma_f32_16x16x32_bf16 v[58:61], v[152:155], v[182:185], v[58:61]
	v_mfma_f32_16x16x32_bf16 v[34:37], v[160:163], v[182:185], v[34:37]
	v_mfma_f32_16x16x32_bf16 v[54:57], v[152:155], v[190:193], v[54:57]
	v_mfma_f32_16x16x32_bf16 v[26:29], v[160:163], v[190:193], v[26:29]
	v_mfma_f32_16x16x32_bf16 v[50:53], v[152:155], v[214:217], v[50:53]
	v_mfma_f32_16x16x32_bf16 v[18:21], v[160:163], v[214:217], v[18:21]
	v_mfma_f32_16x16x32_bf16 v[62:65], v[156:159], v[178:181], v[62:65]
	v_mfma_f32_16x16x32_bf16 v[42:45], v[164:167], v[178:181], v[42:45]
	v_mfma_f32_16x16x32_bf16 v[58:61], v[156:159], v[186:189], v[58:61]
	v_mfma_f32_16x16x32_bf16 v[34:37], v[164:167], v[186:189], v[34:37]
	v_mfma_f32_16x16x32_bf16 v[54:57], v[156:159], v[210:213], v[54:57]
	v_mfma_f32_16x16x32_bf16 v[26:29], v[164:167], v[210:213], v[26:29]
	v_mfma_f32_16x16x32_bf16 v[50:53], v[156:159], v[218:221], v[50:53]
	v_mfma_f32_16x16x32_bf16 v[18:21], v[164:167], v[218:221], v[18:21]
	s_barrier
	s_add_i32 s54, s73, s56
	v_lshl_add_u64 v[172:173], v[172:173], 0, s[42:43]
	s_mov_b32 m0, s54
	ds_read_b128 v[168:171], v177 offset:49152
	ds_read_b128 v[178:181], v177 offset:50176
	ds_read_b128 v[182:185], v177 offset:51200
	ds_read_b128 v[186:189], v177 offset:52224
	ds_read_b128 v[190:193], v177 offset:53248
	ds_read_b128 v[210:213], v177 offset:54272
	ds_read_b128 v[214:217], v177 offset:55296
	ds_read_b128 v[218:221], v177 offset:56320
	global_load_lds_dwordx4 v[172:173], off
	s_add_i32 m0, s54, 0x2000
	s_add_u32 s34, s34, 0x80080
	v_lshl_add_u64 v[172:173], v[194:195], 0, s[42:43]
	s_addc_u32 s35, s35, 0
	s_add_i32 s54, s85, s56
	global_load_lds_dwordx4 v[172:173], off
	v_lshl_add_u64 v[172:173], s[34:35], 0, v[0:1]
	s_mov_b32 m0, s54
	s_nop 0
	global_load_lds_dwordx4 v[172:173], off
	v_lshl_add_u64 v[172:173], s[34:35], 0, v[130:131]
	s_add_i32 m0, s54, 0x2000
	s_nop 0
	global_load_lds_dwordx4 v[172:173], off
	s_nop 0
	s_waitcnt vmcnt(4)
	s_waitcnt lgkmcnt(0)
	s_barrier
	v_mfma_f32_16x16x32_bf16 v[110:113], v[136:139], v[168:171], v[110:113]
	v_mfma_f32_16x16x32_bf16 v[78:81], v[144:147], v[168:171], v[78:81]
	v_mfma_f32_16x16x32_bf16 v[106:109], v[136:139], v[182:185], v[106:109]
	v_mfma_f32_16x16x32_bf16 v[74:77], v[144:147], v[182:185], v[74:77]
	v_mfma_f32_16x16x32_bf16 v[102:105], v[136:139], v[190:193], v[102:105]
	v_mfma_f32_16x16x32_bf16 v[70:73], v[144:147], v[190:193], v[70:73]
	v_mfma_f32_16x16x32_bf16 v[98:101], v[136:139], v[214:217], v[98:101]
	v_mfma_f32_16x16x32_bf16 v[66:69], v[144:147], v[214:217], v[66:69]
	v_mfma_f32_16x16x32_bf16 v[110:113], v[140:143], v[178:181], v[110:113]
	v_mfma_f32_16x16x32_bf16 v[78:81], v[148:151], v[178:181], v[78:81]
	v_mfma_f32_16x16x32_bf16 v[106:109], v[140:143], v[186:189], v[106:109]
	v_mfma_f32_16x16x32_bf16 v[74:77], v[148:151], v[186:189], v[74:77]
	v_mfma_f32_16x16x32_bf16 v[102:105], v[140:143], v[210:213], v[102:105]
	v_mfma_f32_16x16x32_bf16 v[70:73], v[148:151], v[210:213], v[70:73]
	v_mfma_f32_16x16x32_bf16 v[98:101], v[140:143], v[218:221], v[98:101]
	v_mfma_f32_16x16x32_bf16 v[66:69], v[148:151], v[218:221], v[66:69]
	v_mfma_f32_16x16x32_bf16 v[46:49], v[152:155], v[168:171], v[46:49]
	v_mfma_f32_16x16x32_bf16 v[14:17], v[160:163], v[168:171], v[14:17]
	v_mfma_f32_16x16x32_bf16 v[38:41], v[152:155], v[182:185], v[38:41]
	v_mfma_f32_16x16x32_bf16 v[10:13], v[160:163], v[182:185], v[10:13]
	v_mfma_f32_16x16x32_bf16 v[30:33], v[152:155], v[190:193], v[30:33]
	v_mfma_f32_16x16x32_bf16 v[6:9], v[160:163], v[190:193], v[6:9]
	v_mfma_f32_16x16x32_bf16 v[22:25], v[152:155], v[214:217], v[22:25]
	v_mfma_f32_16x16x32_bf16 v[2:5], v[160:163], v[214:217], v[2:5]
	v_mfma_f32_16x16x32_bf16 v[46:49], v[156:159], v[178:181], v[46:49]
	v_mfma_f32_16x16x32_bf16 v[14:17], v[164:167], v[178:181], v[14:17]
	v_mfma_f32_16x16x32_bf16 v[38:41], v[156:159], v[186:189], v[38:41]
	v_mfma_f32_16x16x32_bf16 v[10:13], v[164:167], v[186:189], v[10:13]
	v_mfma_f32_16x16x32_bf16 v[30:33], v[156:159], v[210:213], v[30:33]
	v_mfma_f32_16x16x32_bf16 v[6:9], v[164:167], v[210:213], v[6:9]
	v_mfma_f32_16x16x32_bf16 v[22:25], v[156:159], v[218:221], v[22:25]
	v_mfma_f32_16x16x32_bf16 v[2:5], v[164:167], v[218:221], v[2:5]
	s_barrier
	s_add_u32 s27, s27, 0x100
	s_addc_u32 s71, s71, 0
	s_add_u32 s30, s30, 0x100
	s_addc_u32 s31, s31, 0
	s_cmp_ge_u32 s72, s19
	s_mov_b32 s34, s72
	s_cbranch_scc0 .LBB0_209
	s_and_b64 vcc, exec, s[16:17]
	s_cbranch_vccz .LBB0_212
	s_barrier

; #define PG8_STAGE(bufoff, gbase, voff) do { _Pragma("unroll") for (int _i = 0; _i < 2; ++_i) \
;         __builtin_amdgcn_global_load_lds((const unsigned*)((const char*)(gbase) + (voff)[_i]), (LAS unsigned*)(lds + (bufoff) + ldsw + _i * 8192), 16, 0, 0); } while (0)
; #define PG8_LDA(dst, b, h) do { _Pragma("unroll") for (int m = 0; m < 4; ++m) _Pragma("unroll") for (int k = 0; k < 2; ++k) dst[m][k] = *(const LAS bf16x8*)(lds + PG8_SA(b, h) + aoff + m * 2048 + k * 1024); } while (0)
; #define PG8_LDB(dst, b, h) do { _Pragma("unroll") for (int n = 0; n < 2; ++n) _Pragma("unroll") for (int k = 0; k < 2; ++k) dst[n][k] = *(const LAS bf16x8*)(lds + PG8_SB(b, h) + boff + n * 2048 + k * 1024); } while (0)
; #define PG8_MMA(ai, bj, At, Bt) do { __builtin_amdgcn_s_setprio(1); _Pragma("unroll") for (int m = 0; m < 4; ++m) _Pragma("unroll") for (int n = 0; n < 2; ++n) _Pragma("unroll") for (int k = 0; k < 2; ++k) \
;         acc[ai][bj][m][n] = __builtin_amdgcn_mfma_f32_16x16x32_bf16(Bt[n][k], At[m][k], acc[ai][bj][m][n], 0, 0, 0); __builtin_amdgcn_s_setprio(0); } while (0)
; #define PG8_WAIT_V(n) asm volatile("s_waitcnt vmcnt(" #n ")" ::: "memory")
; #define PG8_WAIT_L(n) asm volatile("s_waitcnt lgkmcnt(" #n ")" ::: "memory")
; #define PG8_BAR __builtin_amdgcn_s_barrier()
; #define PG8_SCHED __builtin_amdgcn_sched_barrier(0)
; template <class Epi, bool ALIGN_EPI>
; __device__ __forceinline__ void gemm_phase(LAS unsigned char* lds, const int tid, const Gemm g, const StaticOrder& S, const Epi& E) {
;     ...
;             const bool last = (t == nt - 2);
;             const char* a1 = cA + (size_t)(t + 1) * kstepA;
;             const char* a2 = last ? nA : cA + (size_t)(t + 2) * kstepA; const char* b2 = last ? nB : cB + (size_t)(t + 2) * kstepB;
;             const char* a3 = a2 + kstepA; const char* b3 = b2 + kstepB;
;             PG8_LDB(B0, 0, 0); PG8_LDB(B1, 0, 1); PG8_SCHED; PG8_LDA(At, 0, 0); PG8_STAGE(PG8_SA(1, 1), a1 + hstepA, voffA);
;             PG8_WAIT_V(8); PG8_WAIT_L(0); PG8_BAR; PG8_MMA(0, 0, At, B0); PG8_MMA(0, 1, At, B1); PG8_BAR; PG8_SCHED;
;             PG8_LDA(At, 0, 1); PG8_STAGE(PG8_SB(0, 0), b2, voffB); PG8_STAGE(PG8_SB(0, 1), b2 + hstepB, voffB); PG8_STAGE(PG8_SA(0, 0), a2, voffA);
;             PG8_WAIT_V(8); PG8_WAIT_L(0); PG8_BAR; PG8_MMA(1, 0, At, B0); PG8_MMA(1, 1, At, B1); PG8_BAR; PG8_SCHED;
.LBB0_263:
	s_add_i32 s5, s5, 2
	s_add_u32 s34, s30, 0xfff80080
	s_addc_u32 s35, s31, -1
	s_add_i32 s94, 0, 0x10000
	s_cmp_eq_u32 s91, s92
	s_cselect_b32 s55, s23, s35
	s_cselect_b32 s54, s22, s34
	v_add_u32_e32 v0, s94, v205
	s_cselect_b32 s35, s25, s36
	s_cselect_b32 s34, s24, s21
	s_add_i32 s96, 0, 0x14000
	ds_read_b128 v[132:135], v0
	ds_read_b128 v[136:139], v0 offset:1024
	ds_read_b128 v[140:143], v0 offset:2048
	ds_read_b128 v[144:147], v0 offset:3072
	v_add_u32_e32 v0, s96, v205
	ds_read_b128 v[148:151], v0
	ds_read_b128 v[152:155], v0 offset:1024
	ds_read_b128 v[156:159], v0 offset:2048
	ds_read_b128 v[160:163], v0 offset:3072
	v_lshl_add_u64 v[2:3], s[30:31], 0, v[220:221]
	s_add_i32 m0, s68, 0xc000
	ds_read_b128 v[164:167], v209
	ds_read_b128 v[168:171], v209 offset:1024
	ds_read_b128 v[172:175], v209 offset:2048
	ds_read_b128 v[176:179], v209 offset:3072
	ds_read_b128 v[180:183], v209 offset:4096
	ds_read_b128 v[184:187], v209 offset:5120
	ds_read_b128 v[188:191], v209 offset:6144
	ds_read_b128 v[192:195], v209 offset:7168
	global_load_lds_dwordx4 v[2:3], off
	v_lshl_add_u64 v[2:3], s[30:31], 0, v[218:219]
	s_add_i32 m0, s68, 0xe000
	s_nop 0
	global_load_lds_dwordx4 v[2:3], off
	s_sub_u32 s98, s30, 0x80000
	s_subb_u32 s99, s31, 0
	v_lshl_add_u64 v[2:3], s[98:99], 0, v[220:221]
	s_mov_b32 m0, s72
	s_nop 0
	global_load_lds_dwordx4 v[2:3], off
	v_lshl_add_u64 v[2:3], s[98:99], 0, v[218:219]
	s_mov_b32 m0, s73
	s_nop 0
	global_load_lds_dwordx4 v[2:3], off
	s_waitcnt vmcnt(8)
	s_waitcnt lgkmcnt(0)
	s_barrier
	v_mfma_f32_16x16x32_bf16 v[128:131], v[132:135], v[164:167], v[128:131]
	v_mfma_f32_16x16x32_bf16 v[124:127], v[140:143], v[164:167], v[124:127]
	v_mfma_f32_16x16x32_bf16 v[112:115], v[132:135], v[172:175], v[112:115]
	v_mfma_f32_16x16x32_bf16 v[108:111], v[140:143], v[172:175], v[108:111]
	v_mfma_f32_16x16x32_bf16 v[96:99], v[132:135], v[180:183], v[96:99]
	v_mfma_f32_16x16x32_bf16 v[92:95], v[140:143], v[180:183], v[92:95]
	v_mfma_f32_16x16x32_bf16 v[80:83], v[132:135], v[188:191], v[80:83]
	v_mfma_f32_16x16x32_bf16 v[76:79], v[140:143], v[188:191], v[76:79]
	v_mfma_f32_16x16x32_bf16 v[128:131], v[136:139], v[168:171], v[128:131]
	v_mfma_f32_16x16x32_bf16 v[124:127], v[144:147], v[168:171], v[124:127]
	v_mfma_f32_16x16x32_bf16 v[112:115], v[136:139], v[176:179], v[112:115]
	v_mfma_f32_16x16x32_bf16 v[108:111], v[144:147], v[176:179], v[108:111]
	v_mfma_f32_16x16x32_bf16 v[96:99], v[136:139], v[184:187], v[96:99]
	v_mfma_f32_16x16x32_bf16 v[92:95], v[144:147], v[184:187], v[92:95]
	v_mfma_f32_16x16x32_bf16 v[80:83], v[136:139], v[192:195], v[80:83]
	v_mfma_f32_16x16x32_bf16 v[76:79], v[144:147], v[192:195], v[76:79]
	v_mfma_f32_16x16x32_bf16 v[120:123], v[148:151], v[164:167], v[120:123]
	v_mfma_f32_16x16x32_bf16 v[116:119], v[156:159], v[164:167], v[116:119]
	v_mfma_f32_16x16x32_bf16 v[104:107], v[148:151], v[172:175], v[104:107]
	v_mfma_f32_16x16x32_bf16 v[100:103], v[156:159], v[172:175], v[100:103]
	v_mfma_f32_16x16x32_bf16 v[88:91], v[148:151], v[180:183], v[88:91]
	v_mfma_f32_16x16x32_bf16 v[84:87], v[156:159], v[180:183], v[84:87]
	v_mfma_f32_16x16x32_bf16 v[72:75], v[148:151], v[188:191], v[72:75]
	v_mfma_f32_16x16x32_bf16 v[68:71], v[156:159], v[188:191], v[68:71]
	v_mfma_f32_16x16x32_bf16 v[120:123], v[152:155], v[168:171], v[120:123]
	v_mfma_f32_16x16x32_bf16 v[116:119], v[160:163], v[168:171], v[116:119]
	v_mfma_f32_16x16x32_bf16 v[104:107], v[152:155], v[176:179], v[104:107]
	v_mfma_f32_16x16x32_bf16 v[100:103], v[160:163], v[176:179], v[100:103]
	v_mfma_f32_16x16x32_bf16 v[88:91], v[152:155], v[184:187], v[88:91]
	v_mfma_f32_16x16x32_bf16 v[84:87], v[160:163], v[184:187], v[84:87]
	v_mfma_f32_16x16x32_bf16 v[72:75], v[152:155], v[192:195], v[72:75]
	v_mfma_f32_16x16x32_bf16 v[68:71], v[160:163], v[192:195], v[68:71]
	s_barrier
	s_add_i32 s94, s94, s67
	v_lshl_add_u64 v[240:241], s[34:35], 0, v[212:213]
	s_mov_b32 m0, s94
	ds_read_b128 v[164:167], v209 offset:16384
	ds_read_b128 v[168:171], v209 offset:17408
	ds_read_b128 v[172:175], v209 offset:18432
	ds_read_b128 v[176:179], v209 offset:19456
	ds_read_b128 v[180:183], v209 offset:20480
	ds_read_b128 v[184:187], v209 offset:21504
	ds_read_b128 v[188:191], v209 offset:22528
	ds_read_b128 v[192:195], v209 offset:23552
	global_load_lds_dwordx4 v[240:241], off
	s_add_i32 m0, s94, 0x2000
	s_add_u32 s94, s34, 0x80000
	v_lshl_add_u64 v[242:243], s[34:35], 0, v[216:217]
	s_addc_u32 s95, s35, 0
	s_add_i32 s96, s96, s67
	global_load_lds_dwordx4 v[242:243], off
	v_lshl_add_u64 v[2:3], s[94:95], 0, v[212:213]
	s_mov_b32 m0, s96
	v_lshl_add_u64 v[244:245], s[54:55], 0, v[210:211]
	global_load_lds_dwordx4 v[2:3], off
	v_lshl_add_u64 v[2:3], s[94:95], 0, v[216:217]
	s_add_i32 m0, s96, 0x2000
	v_lshl_add_u64 v[246:247], s[54:55], 0, v[214:215]
	global_load_lds_dwordx4 v[2:3], off
	s_nop 0
	s_waitcnt vmcnt(4)
	s_waitcnt lgkmcnt(0)
	s_barrier
; #define PG8_STAGE(bufoff, gbase, voff) do { _Pragma("unroll") for (int _i = 0; _i < 2; ++_i) \
;         __builtin_amdgcn_global_load_lds((const unsigned*)((const char*)(gbase) + (voff)[_i]), (LAS unsigned*)(lds + (bufoff) + ldsw + _i * 8192), 16, 0, 0); } while (0)
; #define PG8_LDA(dst, b, h) do { _Pragma("unroll") for (int m = 0; m < 4; ++m) _Pragma("unroll") for (int k = 0; k < 2; ++k) dst[m][k] = *(const LAS bf16x8*)(lds + PG8_SA(b, h) + aoff + m * 2048 + k * 1024); } while (0)
; #define PG8_LDB(dst, b, h) do { _Pragma("unroll") for (int n = 0; n < 2; ++n) _Pragma("unroll") for (int k = 0; k < 2; ++k) dst[n][k] = *(const LAS bf16x8*)(lds + PG8_SB(b, h) + boff + n * 2048 + k * 1024); } while (0)
; #define PG8_MMA(ai, bj, At, Bt) do { __builtin_amdgcn_s_setprio(1); _Pragma("unroll") for (int m = 0; m < 4; ++m) _Pragma("unroll") for (int n = 0; n < 2; ++n) _Pragma("unroll") for (int k = 0; k < 2; ++k) \
;         acc[ai][bj][m][n] = __builtin_amdgcn_mfma_f32_16x16x32_bf16(Bt[n][k], At[m][k], acc[ai][bj][m][n], 0, 0, 0); __builtin_amdgcn_s_setprio(0); } while (0)
; #define PG8_WAIT_V(n) asm volatile("s_waitcnt vmcnt(" #n ")" ::: "memory")
; #define PG8_WAIT_L(n) asm volatile("s_waitcnt lgkmcnt(" #n ")" ::: "memory")
; #define PG8_BAR __builtin_amdgcn_s_barrier()
; #define PG8_SCHED __builtin_amdgcn_sched_barrier(0)
; template <class Epi, bool ALIGN_EPI>
; __device__ __forceinline__ void gemm_phase(LAS unsigned char* lds, const int tid, const Gemm g, const StaticOrder& S, const Epi& E) {
;     ...
;             PG8_WAIT_V(8); PG8_WAIT_L(0); PG8_BAR; PG8_MMA(1, 0, At, B0); PG8_MMA(1, 1, At, B1); PG8_BAR; PG8_SCHED;
;             PG8_LDB(B0, 1, 0); PG8_LDB(B1, 1, 1); PG8_SCHED; PG8_LDA(At, 1, 0); PG8_STAGE(PG8_SA(0, 1), a2 + hstepA, voffA);
;             PG8_WAIT_V(8); PG8_WAIT_L(0); PG8_BAR; PG8_MMA(0, 0, At, B0); PG8_MMA(0, 1, At, B1); PG8_BAR; PG8_SCHED;
	v_mfma_f32_16x16x32_bf16 v[64:67], v[132:135], v[164:167], v[64:67]
	v_mfma_f32_16x16x32_bf16 v[60:63], v[140:143], v[164:167], v[60:63]
	v_mfma_f32_16x16x32_bf16 v[48:51], v[132:135], v[172:175], v[48:51]
	v_mfma_f32_16x16x32_bf16 v[44:47], v[140:143], v[172:175], v[44:47]
	v_mfma_f32_16x16x32_bf16 v[32:35], v[132:135], v[180:183], v[32:35]
	v_mfma_f32_16x16x32_bf16 v[28:31], v[140:143], v[180:183], v[28:31]
	v_mfma_f32_16x16x32_bf16 v[16:19], v[132:135], v[188:191], v[16:19]
	v_mfma_f32_16x16x32_bf16 v[12:15], v[140:143], v[188:191], v[12:15]
	v_mfma_f32_16x16x32_bf16 v[64:67], v[136:139], v[168:171], v[64:67]
	v_mfma_f32_16x16x32_bf16 v[60:63], v[144:147], v[168:171], v[60:63]
	v_mfma_f32_16x16x32_bf16 v[48:51], v[136:139], v[176:179], v[48:51]
	v_mfma_f32_16x16x32_bf16 v[44:47], v[144:147], v[176:179], v[44:47]
	v_mfma_f32_16x16x32_bf16 v[32:35], v[136:139], v[184:187], v[32:35]
	v_mfma_f32_16x16x32_bf16 v[28:31], v[144:147], v[184:187], v[28:31]
	v_mfma_f32_16x16x32_bf16 v[16:19], v[136:139], v[192:195], v[16:19]
	v_mfma_f32_16x16x32_bf16 v[12:15], v[144:147], v[192:195], v[12:15]
	v_mfma_f32_16x16x32_bf16 v[56:59], v[148:151], v[164:167], v[56:59]
	v_mfma_f32_16x16x32_bf16 v[52:55], v[156:159], v[164:167], v[52:55]
	v_mfma_f32_16x16x32_bf16 v[40:43], v[148:151], v[172:175], v[40:43]
	v_mfma_f32_16x16x32_bf16 v[36:39], v[156:159], v[172:175], v[36:39]
	v_mfma_f32_16x16x32_bf16 v[24:27], v[148:151], v[180:183], v[24:27]
	v_mfma_f32_16x16x32_bf16 v[20:23], v[156:159], v[180:183], v[20:23]
	v_mfma_f32_16x16x32_bf16 v[8:11], v[148:151], v[188:191], v[8:11]
	v_mfma_f32_16x16x32_bf16 v[2:5], v[156:159], v[188:191], v[4:7]
	v_mfma_f32_16x16x32_bf16 v[56:59], v[152:155], v[168:171], v[56:59]
	v_mfma_f32_16x16x32_bf16 v[52:55], v[160:163], v[168:171], v[52:55]
	v_mfma_f32_16x16x32_bf16 v[40:43], v[152:155], v[176:179], v[40:43]
	v_mfma_f32_16x16x32_bf16 v[36:39], v[160:163], v[176:179], v[36:39]
	v_mfma_f32_16x16x32_bf16 v[24:27], v[152:155], v[184:187], v[24:27]
	v_mfma_f32_16x16x32_bf16 v[20:23], v[160:163], v[184:187], v[20:23]
	v_mfma_f32_16x16x32_bf16 v[8:11], v[152:155], v[192:195], v[8:11]
	v_mfma_f32_16x16x32_bf16 v[2:5], v[160:163], v[192:195], v[2:5]
	s_barrier
	s_add_i32 s94, 0, 0x18000
	v_add_u32_e32 v0, s94, v205
	s_add_i32 s95, 0, 0x1c000
	ds_read_b128 v[132:135], v0
	ds_read_b128 v[136:139], v0 offset:1024
	ds_read_b128 v[140:143], v0 offset:2048
	ds_read_b128 v[144:147], v0 offset:3072
	v_add_u32_e32 v0, s95, v205
	ds_read_b128 v[148:151], v0
	ds_read_b128 v[152:155], v0 offset:1024
	ds_read_b128 v[156:159], v0 offset:2048
	ds_read_b128 v[160:163], v0 offset:3072
	s_mov_b32 m0, s68
	s_nop 0
	global_load_lds_dwordx4 v[244:245], off
	s_mov_b32 m0, s69
	s_nop 0
	global_load_lds_dwordx4 v[246:247], off
	s_add_u32 s54, s54, 0x80000
	s_addc_u32 s55, s55, 0
	s_mov_b32 m0, s70
	v_lshl_add_u64 v[6:7], s[54:55], 0, v[210:211]
	ds_read_b128 v[164:167], v209 offset:32768
	ds_read_b128 v[168:171], v209 offset:33792
	ds_read_b128 v[172:175], v209 offset:34816
	ds_read_b128 v[176:179], v209 offset:35840
	ds_read_b128 v[180:183], v209 offset:36864
	ds_read_b128 v[184:187], v209 offset:37888
	ds_read_b128 v[188:191], v209 offset:38912
	ds_read_b128 v[192:195], v209 offset:39936
	global_load_lds_dwordx4 v[6:7], off
	v_lshl_add_u64 v[6:7], s[54:55], 0, v[214:215]
	s_mov_b32 m0, s71
	s_nop 0
	global_load_lds_dwordx4 v[6:7], off
	s_waitcnt vmcnt(8)
	s_waitcnt lgkmcnt(0)
	s_barrier
; #define PG8_STAGE(bufoff, gbase, voff) do { _Pragma("unroll") for (int _i = 0; _i < 2; ++_i) \
;         __builtin_amdgcn_global_load_lds((const unsigned*)((const char*)(gbase) + (voff)[_i]), (LAS unsigned*)(lds + (bufoff) + ldsw + _i * 8192), 16, 0, 0); } while (0)
; #define PG8_LDA(dst, b, h) do { _Pragma("unroll") for (int m = 0; m < 4; ++m) _Pragma("unroll") for (int k = 0; k < 2; ++k) dst[m][k] = *(const LAS bf16x8*)(lds + PG8_SA(b, h) + aoff + m * 2048 + k * 1024); } while (0)
; #define PG8_MMA(ai, bj, At, Bt) do { __builtin_amdgcn_s_setprio(1); _Pragma("unroll") for (int m = 0; m < 4; ++m) _Pragma("unroll") for (int n = 0; n < 2; ++n) _Pragma("unroll") for (int k = 0; k < 2; ++k) \
;         acc[ai][bj][m][n] = __builtin_amdgcn_mfma_f32_16x16x32_bf16(Bt[n][k], At[m][k], acc[ai][bj][m][n], 0, 0, 0); __builtin_amdgcn_s_setprio(0); } while (0)
; #define PG8_WAIT_V(n) asm volatile("s_waitcnt vmcnt(" #n ")" ::: "memory")
; #define PG8_WAIT_L(n) asm volatile("s_waitcnt lgkmcnt(" #n ")" ::: "memory")
; #define PG8_BAR __builtin_amdgcn_s_barrier()
; #define PG8_SCHED __builtin_amdgcn_sched_barrier(0)
; template <class Epi, bool ALIGN_EPI>
; __device__ __forceinline__ void gemm_phase(LAS unsigned char* lds, const int tid, const Gemm g, const StaticOrder& S, const Epi& E) {
;     ...
;             PG8_WAIT_V(8); PG8_WAIT_L(0); PG8_BAR; PG8_MMA(0, 0, At, B0); PG8_MMA(0, 1, At, B1); PG8_BAR; PG8_SCHED;
;             PG8_LDA(At, 1, 1); PG8_STAGE(PG8_SB(1, 0), b3, voffB); PG8_STAGE(PG8_SB(1, 1), b3 + hstepB, voffB); PG8_STAGE(PG8_SA(1, 0), a3, voffA);
;             PG8_WAIT_V(8); PG8_WAIT_L(0); PG8_BAR; PG8_MMA(1, 0, At, B0); PG8_MMA(1, 1, At, B1); PG8_BAR; PG8_SCHED;
;         }
	v_mfma_f32_16x16x32_bf16 v[128:131], v[132:135], v[164:167], v[128:131]
	v_mfma_f32_16x16x32_bf16 v[124:127], v[140:143], v[164:167], v[124:127]
	v_mfma_f32_16x16x32_bf16 v[112:115], v[132:135], v[172:175], v[112:115]
	v_mfma_f32_16x16x32_bf16 v[108:111], v[140:143], v[172:175], v[108:111]
	v_mfma_f32_16x16x32_bf16 v[96:99], v[132:135], v[180:183], v[96:99]
	v_mfma_f32_16x16x32_bf16 v[92:95], v[140:143], v[180:183], v[92:95]
	v_mfma_f32_16x16x32_bf16 v[80:83], v[132:135], v[188:191], v[80:83]
	v_mfma_f32_16x16x32_bf16 v[76:79], v[140:143], v[188:191], v[76:79]
	v_mfma_f32_16x16x32_bf16 v[128:131], v[136:139], v[168:171], v[128:131]
	v_mfma_f32_16x16x32_bf16 v[124:127], v[144:147], v[168:171], v[124:127]
	v_mfma_f32_16x16x32_bf16 v[112:115], v[136:139], v[176:179], v[112:115]
	v_mfma_f32_16x16x32_bf16 v[108:111], v[144:147], v[176:179], v[108:111]
	v_mfma_f32_16x16x32_bf16 v[96:99], v[136:139], v[184:187], v[96:99]
	v_mfma_f32_16x16x32_bf16 v[92:95], v[144:147], v[184:187], v[92:95]
	v_mfma_f32_16x16x32_bf16 v[80:83], v[136:139], v[192:195], v[80:83]
	v_mfma_f32_16x16x32_bf16 v[76:79], v[144:147], v[192:195], v[76:79]
	v_mfma_f32_16x16x32_bf16 v[120:123], v[148:151], v[164:167], v[120:123]
	v_mfma_f32_16x16x32_bf16 v[116:119], v[156:159], v[164:167], v[116:119]
	v_mfma_f32_16x16x32_bf16 v[104:107], v[148:151], v[172:175], v[104:107]
	v_mfma_f32_16x16x32_bf16 v[100:103], v[156:159], v[172:175], v[100:103]
	v_mfma_f32_16x16x32_bf16 v[88:91], v[148:151], v[180:183], v[88:91]
	v_mfma_f32_16x16x32_bf16 v[84:87], v[156:159], v[180:183], v[84:87]
	v_mfma_f32_16x16x32_bf16 v[72:75], v[148:151], v[188:191], v[72:75]
	v_mfma_f32_16x16x32_bf16 v[68:71], v[156:159], v[188:191], v[68:71]
	v_mfma_f32_16x16x32_bf16 v[120:123], v[152:155], v[168:171], v[120:123]
	v_mfma_f32_16x16x32_bf16 v[116:119], v[160:163], v[168:171], v[116:119]
	v_mfma_f32_16x16x32_bf16 v[104:107], v[152:155], v[176:179], v[104:107]
	v_mfma_f32_16x16x32_bf16 v[100:103], v[160:163], v[176:179], v[100:103]
	v_mfma_f32_16x16x32_bf16 v[88:91], v[152:155], v[184:187], v[88:91]
	v_mfma_f32_16x16x32_bf16 v[84:87], v[160:163], v[184:187], v[84:87]
	v_mfma_f32_16x16x32_bf16 v[72:75], v[152:155], v[192:195], v[72:75]
	v_mfma_f32_16x16x32_bf16 v[68:71], v[160:163], v[192:195], v[68:71]
	s_barrier
	s_add_i32 s54, s94, s67
	v_lshl_add_u64 v[6:7], v[240:241], 0, s[42:43]
	s_mov_b32 m0, s54
	ds_read_b128 v[164:167], v209 offset:49152
	ds_read_b128 v[168:171], v209 offset:50176
	ds_read_b128 v[172:175], v209 offset:51200
	ds_read_b128 v[176:179], v209 offset:52224
	ds_read_b128 v[180:183], v209 offset:53248
	ds_read_b128 v[184:187], v209 offset:54272
	ds_read_b128 v[188:191], v209 offset:55296
	ds_read_b128 v[192:195], v209 offset:56320
	global_load_lds_dwordx4 v[6:7], off
	s_add_i32 m0, s54, 0x2000
	s_add_u32 s34, s34, 0x80080
	v_lshl_add_u64 v[6:7], v[242:243], 0, s[42:43]
	s_addc_u32 s35, s35, 0
	s_add_i32 s54, s95, s67
	global_load_lds_dwordx4 v[6:7], off
	v_lshl_add_u64 v[6:7], s[34:35], 0, v[212:213]
	s_mov_b32 m0, s54
	s_nop 0
	global_load_lds_dwordx4 v[6:7], off
	v_lshl_add_u64 v[6:7], s[34:35], 0, v[216:217]
	s_add_i32 m0, s54, 0x2000
	s_nop 0
	global_load_lds_dwordx4 v[6:7], off
	s_nop 0
	s_waitcnt vmcnt(4)
	s_waitcnt lgkmcnt(0)
	s_barrier
	v_mfma_f32_16x16x32_bf16 v[64:67], v[132:135], v[164:167], v[64:67]
	v_mfma_f32_16x16x32_bf16 v[60:63], v[140:143], v[164:167], v[60:63]
	v_mfma_f32_16x16x32_bf16 v[48:51], v[132:135], v[172:175], v[48:51]
	v_mfma_f32_16x16x32_bf16 v[44:47], v[140:143], v[172:175], v[44:47]
	v_mfma_f32_16x16x32_bf16 v[32:35], v[132:135], v[180:183], v[32:35]
	v_mfma_f32_16x16x32_bf16 v[28:31], v[140:143], v[180:183], v[28:31]
	v_mfma_f32_16x16x32_bf16 v[16:19], v[132:135], v[188:191], v[16:19]
	v_mfma_f32_16x16x32_bf16 v[12:15], v[140:143], v[188:191], v[12:15]
	v_mfma_f32_16x16x32_bf16 v[64:67], v[136:139], v[168:171], v[64:67]
	v_mfma_f32_16x16x32_bf16 v[60:63], v[144:147], v[168:171], v[60:63]
	v_mfma_f32_16x16x32_bf16 v[48:51], v[136:139], v[176:179], v[48:51]
	v_mfma_f32_16x16x32_bf16 v[44:47], v[144:147], v[176:179], v[44:47]
	v_mfma_f32_16x16x32_bf16 v[32:35], v[136:139], v[184:187], v[32:35]
	v_mfma_f32_16x16x32_bf16 v[28:31], v[144:147], v[184:187], v[28:31]
	v_mfma_f32_16x16x32_bf16 v[16:19], v[136:139], v[192:195], v[16:19]
	v_mfma_f32_16x16x32_bf16 v[12:15], v[144:147], v[192:195], v[12:15]
	v_mfma_f32_16x16x32_bf16 v[56:59], v[148:151], v[164:167], v[56:59]
	v_mfma_f32_16x16x32_bf16 v[52:55], v[156:159], v[164:167], v[52:55]
	v_mfma_f32_16x16x32_bf16 v[40:43], v[148:151], v[172:175], v[40:43]
	v_mfma_f32_16x16x32_bf16 v[36:39], v[156:159], v[172:175], v[36:39]
	v_mfma_f32_16x16x32_bf16 v[24:27], v[148:151], v[180:183], v[24:27]
	v_mfma_f32_16x16x32_bf16 v[20:23], v[156:159], v[180:183], v[20:23]
	v_mfma_f32_16x16x32_bf16 v[6:9], v[148:151], v[188:191], v[8:11]
	v_mfma_f32_16x16x32_bf16 v[2:5], v[156:159], v[188:191], v[2:5]
	v_mfma_f32_16x16x32_bf16 v[56:59], v[152:155], v[168:171], v[56:59]
	v_mfma_f32_16x16x32_bf16 v[52:55], v[160:163], v[168:171], v[52:55]
	v_mfma_f32_16x16x32_bf16 v[40:43], v[152:155], v[176:179], v[40:43]
	v_mfma_f32_16x16x32_bf16 v[36:39], v[160:163], v[176:179], v[36:39]
	v_mfma_f32_16x16x32_bf16 v[24:27], v[152:155], v[184:187], v[24:27]
	v_mfma_f32_16x16x32_bf16 v[20:23], v[160:163], v[184:187], v[20:23]
	v_mfma_f32_16x16x32_bf16 v[8:11], v[152:155], v[192:195], v[6:9]
	v_mfma_f32_16x16x32_bf16 v[4:7], v[160:163], v[192:195], v[2:5]
	s_barrier
	s_add_u32 s92, s92, 0x400
	s_addc_u32 s93, s93, 0
	s_add_u32 s21, s21, 0x100
	s_addc_u32 s36, s36, 0
	s_add_u32 s30, s30, 0x100
	s_addc_u32 s31, s31, 0
	s_cmp_ge_u32 s5, s19
	s_cbranch_scc1 .LBB0_266

; #define PG8_STAGE(bufoff, gbase, voff) do { _Pragma("unroll") for (int _i = 0; _i < 2; ++_i) \
;         __builtin_amdgcn_global_load_lds((const unsigned*)((const char*)(gbase) + (voff)[_i]), (LAS unsigned*)(lds + (bufoff) + ldsw + _i * 8192), 16, 0, 0); } while (0)
; #define PG8_LDA(dst, b, h) do { _Pragma("unroll") for (int m = 0; m < 4; ++m) _Pragma("unroll") for (int k = 0; k < 2; ++k) dst[m][k] = *(const LAS bf16x8*)(lds + PG8_SA(b, h) + aoff + m * 2048 + k * 1024); } while (0)
; #define PG8_LDB(dst, b, h) do { _Pragma("unroll") for (int n = 0; n < 2; ++n) _Pragma("unroll") for (int k = 0; k < 2; ++k) dst[n][k] = *(const LAS bf16x8*)(lds + PG8_SB(b, h) + boff + n * 2048 + k * 1024); } while (0)
; #define PG8_MMA(ai, bj, At, Bt) do { __builtin_amdgcn_s_setprio(1); _Pragma("unroll") for (int m = 0; m < 4; ++m) _Pragma("unroll") for (int n = 0; n < 2; ++n) _Pragma("unroll") for (int k = 0; k < 2; ++k) \
;         acc[ai][bj][m][n] = __builtin_amdgcn_mfma_f32_16x16x32_bf16(Bt[n][k], At[m][k], acc[ai][bj][m][n], 0, 0, 0); __builtin_amdgcn_s_setprio(0); } while (0)
; #define PG8_WAIT_V(n) asm volatile("s_waitcnt vmcnt(" #n ")" ::: "memory")
; #define PG8_WAIT_L(n) asm volatile("s_waitcnt lgkmcnt(" #n ")" ::: "memory")
; #define PG8_BAR __builtin_amdgcn_s_barrier()
; #define PG8_SCHED __builtin_amdgcn_sched_barrier(0)
; template <class Epi, bool ALIGN_EPI>
; __device__ __forceinline__ void gemm_phase(LAS unsigned char* lds, const int tid, const Gemm g, const StaticOrder& S, const Epi& E) {
;     ...
;             const bool last = (t == nt - 2);
;             const char* a1 = cA + (size_t)(t + 1) * kstepA;
;             const char* a2 = last ? nA : cA + (size_t)(t + 2) * kstepA; const char* b2 = last ? nB : cB + (size_t)(t + 2) * kstepB;
;             const char* a3 = a2 + kstepA; const char* b3 = b2 + kstepB;
;             PG8_LDB(B0, 0, 0); PG8_LDB(B1, 0, 1); PG8_SCHED; PG8_LDA(At, 0, 0); PG8_STAGE(PG8_SA(1, 1), a1 + hstepA, voffA);
;             PG8_WAIT_V(8); PG8_WAIT_L(0); PG8_BAR; PG8_MMA(0, 0, At, B0); PG8_MMA(0, 1, At, B1); PG8_BAR; PG8_SCHED;
;             PG8_LDA(At, 0, 1); PG8_STAGE(PG8_SB(0, 0), b2, voffB); PG8_STAGE(PG8_SB(0, 1), b2 + hstepB, voffB); PG8_STAGE(PG8_SA(0, 0), a2, voffA);
;             PG8_WAIT_V(8); PG8_WAIT_L(0); PG8_BAR; PG8_MMA(1, 0, At, B0); PG8_MMA(1, 1, At, B1); PG8_BAR; PG8_SCHED;
.LBB0_667:
	s_add_u32 s22, s20, 0xfff80080
	s_addc_u32 s23, s21, -1
	s_add_i32 s49, 0, 0x10000
	s_cmp_eq_u32 s19, 28
	s_cselect_b32 s25, s15, s23
	s_cselect_b32 s24, s14, s22
	v_add_u32_e32 v0, s49, v173
	s_cselect_b32 s23, s17, s13
	s_cselect_b32 s22, s16, s11
	s_add_i32 s52, 0, 0x14000
	ds_read_b128 v[130:133], v0
	ds_read_b128 v[134:137], v0 offset:1024
	ds_read_b128 v[138:141], v0 offset:2048
	ds_read_b128 v[142:145], v0 offset:3072
	v_add_u32_e32 v0, s52, v173
	ds_read_b128 v[158:161], v0
	ds_read_b128 v[162:165], v0 offset:1024
	ds_read_b128 v[166:169], v0 offset:2048
	ds_read_b128 v[178:181], v0 offset:3072
	v_lshl_add_u64 v[170:171], s[20:21], 0, v[156:157]
	s_add_i32 m0, s28, 0xc000
	ds_read_b128 v[182:185], v176
	ds_read_b128 v[186:189], v176 offset:1024
	ds_read_b128 v[190:193], v176 offset:2048
	ds_read_b128 v[208:211], v176 offset:3072
	ds_read_b128 v[212:215], v176 offset:4096
	ds_read_b128 v[216:219], v176 offset:5120
	ds_read_b128 v[220:223], v176 offset:6144
	ds_read_b128 v[240:243], v176 offset:7168
	global_load_lds_dwordx4 v[170:171], off
	v_lshl_add_u64 v[170:171], s[20:21], 0, v[154:155]
	s_add_i32 m0, s28, 0xe000
	s_nop 0
	global_load_lds_dwordx4 v[170:171], off
	s_sub_u32 s98, s20, 0x80000
	s_subb_u32 s99, s21, 0
	v_lshl_add_u64 v[170:171], s[98:99], 0, v[156:157]
	s_mov_b32 m0, s34
	s_nop 0
	global_load_lds_dwordx4 v[170:171], off
	v_lshl_add_u64 v[170:171], s[98:99], 0, v[154:155]
	s_mov_b32 m0, s35
	s_nop 0
	global_load_lds_dwordx4 v[170:171], off
	s_waitcnt vmcnt(8)
	s_waitcnt lgkmcnt(0)
	s_barrier
	v_mfma_f32_16x16x32_bf16 v[126:129], v[130:133], v[182:185], v[126:129]
	v_mfma_f32_16x16x32_bf16 v[122:125], v[138:141], v[182:185], v[122:125]
	v_mfma_f32_16x16x32_bf16 v[118:121], v[130:133], v[190:193], v[118:121]
	v_mfma_f32_16x16x32_bf16 v[114:117], v[138:141], v[190:193], v[114:117]
	v_mfma_f32_16x16x32_bf16 v[102:105], v[130:133], v[212:215], v[102:105]
	v_mfma_f32_16x16x32_bf16 v[98:101], v[138:141], v[212:215], v[98:101]
	v_mfma_f32_16x16x32_bf16 v[86:89], v[130:133], v[220:223], v[86:89]
	v_mfma_f32_16x16x32_bf16 v[82:85], v[138:141], v[220:223], v[82:85]
	v_mfma_f32_16x16x32_bf16 v[126:129], v[134:137], v[186:189], v[126:129]
	v_mfma_f32_16x16x32_bf16 v[122:125], v[142:145], v[186:189], v[122:125]
	v_mfma_f32_16x16x32_bf16 v[118:121], v[134:137], v[208:211], v[118:121]
	v_mfma_f32_16x16x32_bf16 v[114:117], v[142:145], v[208:211], v[114:117]
	v_mfma_f32_16x16x32_bf16 v[102:105], v[134:137], v[216:219], v[102:105]
	v_mfma_f32_16x16x32_bf16 v[98:101], v[142:145], v[216:219], v[98:101]
	v_mfma_f32_16x16x32_bf16 v[86:89], v[134:137], v[240:243], v[86:89]
	v_mfma_f32_16x16x32_bf16 v[82:85], v[142:145], v[240:243], v[82:85]
	v_mfma_f32_16x16x32_bf16 v[110:113], v[158:161], v[182:185], v[110:113]
	v_mfma_f32_16x16x32_bf16 v[106:109], v[166:169], v[182:185], v[106:109]
	v_mfma_f32_16x16x32_bf16 v[94:97], v[158:161], v[190:193], v[94:97]
	v_mfma_f32_16x16x32_bf16 v[90:93], v[166:169], v[190:193], v[90:93]
	v_mfma_f32_16x16x32_bf16 v[78:81], v[158:161], v[212:215], v[78:81]
	v_mfma_f32_16x16x32_bf16 v[74:77], v[166:169], v[212:215], v[74:77]
	v_mfma_f32_16x16x32_bf16 v[70:73], v[158:161], v[220:223], v[70:73]
	v_mfma_f32_16x16x32_bf16 v[66:69], v[166:169], v[220:223], v[66:69]
	v_mfma_f32_16x16x32_bf16 v[110:113], v[162:165], v[186:189], v[110:113]
	v_mfma_f32_16x16x32_bf16 v[106:109], v[178:181], v[186:189], v[106:109]
	v_mfma_f32_16x16x32_bf16 v[94:97], v[162:165], v[208:211], v[94:97]
	v_mfma_f32_16x16x32_bf16 v[90:93], v[178:181], v[208:211], v[90:93]
	v_mfma_f32_16x16x32_bf16 v[78:81], v[162:165], v[216:219], v[78:81]
	v_mfma_f32_16x16x32_bf16 v[74:77], v[178:181], v[216:219], v[74:77]
	v_mfma_f32_16x16x32_bf16 v[70:73], v[162:165], v[240:243], v[70:73]
	v_mfma_f32_16x16x32_bf16 v[66:69], v[178:181], v[240:243], v[66:69]
	s_barrier
	s_add_i32 s49, s49, s27
	v_lshl_add_u64 v[170:171], s[22:23], 0, v[148:149]
	s_mov_b32 m0, s49
	ds_read_b128 v[182:185], v176 offset:16384
	ds_read_b128 v[186:189], v176 offset:17408
	ds_read_b128 v[190:193], v176 offset:18432
	ds_read_b128 v[208:211], v176 offset:19456
	ds_read_b128 v[212:215], v176 offset:20480
	ds_read_b128 v[216:219], v176 offset:21504
	ds_read_b128 v[220:223], v176 offset:22528
	ds_read_b128 v[240:243], v176 offset:23552
	global_load_lds_dwordx4 v[170:171], off
	s_add_i32 m0, s49, 0x2000
	s_add_u32 s54, s22, 0x80000
	v_lshl_add_u64 v[194:195], s[22:23], 0, v[152:153]
	s_addc_u32 s55, s23, 0
	s_add_i32 s49, s52, s27
	global_load_lds_dwordx4 v[194:195], off
	v_lshl_add_u64 v[224:225], s[54:55], 0, v[148:149]
	s_mov_b32 m0, s49
	v_lshl_add_u64 v[244:245], s[24:25], 0, v[150:151]
	global_load_lds_dwordx4 v[224:225], off
	v_lshl_add_u64 v[224:225], s[54:55], 0, v[152:153]
	s_add_i32 m0, s49, 0x2000
	s_nop 0
	global_load_lds_dwordx4 v[224:225], off
	v_lshl_add_u64 v[224:225], s[24:25], 0, v[146:147]
	s_waitcnt vmcnt(4)
	s_waitcnt lgkmcnt(0)
	s_barrier
; #define PG8_STAGE(bufoff, gbase, voff) do { _Pragma("unroll") for (int _i = 0; _i < 2; ++_i) \
;         __builtin_amdgcn_global_load_lds((const unsigned*)((const char*)(gbase) + (voff)[_i]), (LAS unsigned*)(lds + (bufoff) + ldsw + _i * 8192), 16, 0, 0); } while (0)
; #define PG8_LDA(dst, b, h) do { _Pragma("unroll") for (int m = 0; m < 4; ++m) _Pragma("unroll") for (int k = 0; k < 2; ++k) dst[m][k] = *(const LAS bf16x8*)(lds + PG8_SA(b, h) + aoff + m * 2048 + k * 1024); } while (0)
; #define PG8_LDB(dst, b, h) do { _Pragma("unroll") for (int n = 0; n < 2; ++n) _Pragma("unroll") for (int k = 0; k < 2; ++k) dst[n][k] = *(const LAS bf16x8*)(lds + PG8_SB(b, h) + boff + n * 2048 + k * 1024); } while (0)
; #define PG8_MMA(ai, bj, At, Bt) do { __builtin_amdgcn_s_setprio(1); _Pragma("unroll") for (int m = 0; m < 4; ++m) _Pragma("unroll") for (int n = 0; n < 2; ++n) _Pragma("unroll") for (int k = 0; k < 2; ++k) \
;         acc[ai][bj][m][n] = __builtin_amdgcn_mfma_f32_16x16x32_bf16(Bt[n][k], At[m][k], acc[ai][bj][m][n], 0, 0, 0); __builtin_amdgcn_s_setprio(0); } while (0)
; #define PG8_WAIT_V(n) asm volatile("s_waitcnt vmcnt(" #n ")" ::: "memory")
; template <class Epi, bool ALIGN_EPI>
; __device__ __forceinline__ void gemm_phase(LAS unsigned char* lds, const int tid, const Gemm g, const StaticOrder& S, const Epi& E) {
;     ...
;             PG8_LDB(B0, 0, 0); PG8_LDB(B1, 0, 1); PG8_SCHED; PG8_LDA(At, 0, 0); PG8_STAGE(PG8_SA(1, 1), a1 + hstepA, voffA);
;             PG8_WAIT_V(8); PG8_WAIT_L(0); PG8_BAR; PG8_MMA(0, 0, At, B0); PG8_MMA(0, 1, At, B1); PG8_BAR; PG8_SCHED;
;             PG8_LDA(At, 0, 1); PG8_STAGE(PG8_SB(0, 0), b2, voffB); PG8_STAGE(PG8_SB(0, 1), b2 + hstepB, voffB); PG8_STAGE(PG8_SA(0, 0), a2, voffA);
;             PG8_WAIT_V(8); PG8_WAIT_L(0); PG8_BAR; PG8_MMA(1, 0, At, B0); PG8_MMA(1, 1, At, B1); PG8_BAR; PG8_SCHED;
;             PG8_LDB(B0, 1, 0); PG8_LDB(B1, 1, 1); PG8_SCHED; PG8_LDA(At, 1, 0); PG8_STAGE(PG8_SA(0, 1), a2 + hstepA, voffA);
;             PG8_WAIT_V(8); PG8_WAIT_L(0); PG8_BAR; PG8_MMA(0, 0, At, B0); PG8_MMA(0, 1, At, B1); PG8_BAR; PG8_SCHED;
;             PG8_LDA(At, 1, 1); PG8_STAGE(PG8_SB(1, 0), b3, voffB); PG8_STAGE(PG8_SB(1, 1), b3 + hstepB, voffB); PG8_STAGE(PG8_SA(1, 0), a3, voffA);
;             PG8_WAIT_V(8); PG8_WAIT_L(0); PG8_BAR; PG8_MMA(1, 0, At, B0); PG8_MMA(1, 1, At, B1); PG8_BAR; PG8_SCHED;
	v_mfma_f32_16x16x32_bf16 v[62:65], v[130:133], v[182:185], v[62:65]
	v_mfma_f32_16x16x32_bf16 v[58:61], v[138:141], v[182:185], v[58:61]
	v_mfma_f32_16x16x32_bf16 v[54:57], v[130:133], v[190:193], v[54:57]
	v_mfma_f32_16x16x32_bf16 v[50:53], v[138:141], v[190:193], v[50:53]
	v_mfma_f32_16x16x32_bf16 v[38:41], v[130:133], v[212:215], v[38:41]
	v_mfma_f32_16x16x32_bf16 v[34:37], v[138:141], v[212:215], v[34:37]
	v_mfma_f32_16x16x32_bf16 v[22:25], v[130:133], v[220:223], v[22:25]
	v_mfma_f32_16x16x32_bf16 v[18:21], v[138:141], v[220:223], v[18:21]
	v_mfma_f32_16x16x32_bf16 v[62:65], v[134:137], v[186:189], v[62:65]
	v_mfma_f32_16x16x32_bf16 v[58:61], v[142:145], v[186:189], v[58:61]
	v_mfma_f32_16x16x32_bf16 v[54:57], v[134:137], v[208:211], v[54:57]
	v_mfma_f32_16x16x32_bf16 v[50:53], v[142:145], v[208:211], v[50:53]
	v_mfma_f32_16x16x32_bf16 v[38:41], v[134:137], v[216:219], v[38:41]
	v_mfma_f32_16x16x32_bf16 v[34:37], v[142:145], v[216:219], v[34:37]
	v_mfma_f32_16x16x32_bf16 v[22:25], v[134:137], v[240:243], v[22:25]
	v_mfma_f32_16x16x32_bf16 v[18:21], v[142:145], v[240:243], v[18:21]
	v_mfma_f32_16x16x32_bf16 v[46:49], v[158:161], v[182:185], v[46:49]
	v_mfma_f32_16x16x32_bf16 v[42:45], v[166:169], v[182:185], v[42:45]
	v_mfma_f32_16x16x32_bf16 v[30:33], v[158:161], v[190:193], v[30:33]
	v_mfma_f32_16x16x32_bf16 v[26:29], v[166:169], v[190:193], v[26:29]
	v_mfma_f32_16x16x32_bf16 v[14:17], v[158:161], v[212:215], v[14:17]
	v_mfma_f32_16x16x32_bf16 v[10:13], v[166:169], v[212:215], v[10:13]
	v_mfma_f32_16x16x32_bf16 v[6:9], v[158:161], v[220:223], v[6:9]
	v_mfma_f32_16x16x32_bf16 v[2:5], v[166:169], v[220:223], v[2:5]
	v_mfma_f32_16x16x32_bf16 v[46:49], v[162:165], v[186:189], v[46:49]
	v_mfma_f32_16x16x32_bf16 v[42:45], v[178:181], v[186:189], v[42:45]
	v_mfma_f32_16x16x32_bf16 v[30:33], v[162:165], v[208:211], v[30:33]
	v_mfma_f32_16x16x32_bf16 v[26:29], v[178:181], v[208:211], v[26:29]
	v_mfma_f32_16x16x32_bf16 v[14:17], v[162:165], v[216:219], v[14:17]
	v_mfma_f32_16x16x32_bf16 v[10:13], v[178:181], v[216:219], v[10:13]
	v_mfma_f32_16x16x32_bf16 v[6:9], v[162:165], v[240:243], v[6:9]
	v_mfma_f32_16x16x32_bf16 v[2:5], v[178:181], v[240:243], v[2:5]
	s_barrier
	s_add_i32 s49, 0, 0x18000
	v_add_u32_e32 v0, s49, v173
	s_add_i32 s52, 0, 0x1c000
	ds_read_b128 v[130:133], v0
	ds_read_b128 v[134:137], v0 offset:1024
	ds_read_b128 v[138:141], v0 offset:2048
	ds_read_b128 v[142:145], v0 offset:3072
	v_add_u32_e32 v0, s52, v173
	ds_read_b128 v[158:161], v0
	ds_read_b128 v[162:165], v0 offset:1024
	ds_read_b128 v[166:169], v0 offset:2048
	ds_read_b128 v[178:181], v0 offset:3072
	s_mov_b32 m0, s28
	s_nop 0
	global_load_lds_dwordx4 v[224:225], off
	s_mov_b32 m0, s29
	s_nop 0
	global_load_lds_dwordx4 v[244:245], off
	s_add_u32 s24, s24, 0x80000
	s_addc_u32 s25, s25, 0
	s_mov_b32 m0, s30
	v_lshl_add_u64 v[246:247], s[24:25], 0, v[146:147]
	ds_read_b128 v[182:185], v176 offset:32768
	ds_read_b128 v[186:189], v176 offset:33792
	ds_read_b128 v[190:193], v176 offset:34816
	ds_read_b128 v[208:211], v176 offset:35840
	ds_read_b128 v[212:215], v176 offset:36864
	ds_read_b128 v[216:219], v176 offset:37888
	ds_read_b128 v[220:223], v176 offset:38912
	ds_read_b128 v[240:243], v176 offset:39936
	global_load_lds_dwordx4 v[246:247], off
	v_lshl_add_u64 v[246:247], s[24:25], 0, v[150:151]
	s_mov_b32 m0, s31
	s_nop 0
	global_load_lds_dwordx4 v[246:247], off
	s_waitcnt vmcnt(8)
	s_waitcnt lgkmcnt(0)
	s_barrier
	v_mfma_f32_16x16x32_bf16 v[126:129], v[130:133], v[182:185], v[126:129]
	v_mfma_f32_16x16x32_bf16 v[122:125], v[138:141], v[182:185], v[122:125]
	v_mfma_f32_16x16x32_bf16 v[118:121], v[130:133], v[190:193], v[118:121]
	v_mfma_f32_16x16x32_bf16 v[114:117], v[138:141], v[190:193], v[114:117]
	v_mfma_f32_16x16x32_bf16 v[102:105], v[130:133], v[212:215], v[102:105]
	v_mfma_f32_16x16x32_bf16 v[98:101], v[138:141], v[212:215], v[98:101]
	v_mfma_f32_16x16x32_bf16 v[86:89], v[130:133], v[220:223], v[86:89]
	v_mfma_f32_16x16x32_bf16 v[82:85], v[138:141], v[220:223], v[82:85]
	v_mfma_f32_16x16x32_bf16 v[126:129], v[134:137], v[186:189], v[126:129]
	v_mfma_f32_16x16x32_bf16 v[122:125], v[142:145], v[186:189], v[122:125]
	v_mfma_f32_16x16x32_bf16 v[118:121], v[134:137], v[208:211], v[118:121]
	v_mfma_f32_16x16x32_bf16 v[114:117], v[142:145], v[208:211], v[114:117]
	v_mfma_f32_16x16x32_bf16 v[102:105], v[134:137], v[216:219], v[102:105]
	v_mfma_f32_16x16x32_bf16 v[98:101], v[142:145], v[216:219], v[98:101]
	v_mfma_f32_16x16x32_bf16 v[86:89], v[134:137], v[240:243], v[86:89]
	v_mfma_f32_16x16x32_bf16 v[82:85], v[142:145], v[240:243], v[82:85]
	v_mfma_f32_16x16x32_bf16 v[110:113], v[158:161], v[182:185], v[110:113]
	v_mfma_f32_16x16x32_bf16 v[106:109], v[166:169], v[182:185], v[106:109]
	v_mfma_f32_16x16x32_bf16 v[94:97], v[158:161], v[190:193], v[94:97]
	v_mfma_f32_16x16x32_bf16 v[90:93], v[166:169], v[190:193], v[90:93]
	v_mfma_f32_16x16x32_bf16 v[78:81], v[158:161], v[212:215], v[78:81]
	v_mfma_f32_16x16x32_bf16 v[74:77], v[166:169], v[212:215], v[74:77]
	v_mfma_f32_16x16x32_bf16 v[70:73], v[158:161], v[220:223], v[70:73]
	v_mfma_f32_16x16x32_bf16 v[66:69], v[166:169], v[220:223], v[66:69]
	v_mfma_f32_16x16x32_bf16 v[110:113], v[162:165], v[186:189], v[110:113]
	v_mfma_f32_16x16x32_bf16 v[106:109], v[178:181], v[186:189], v[106:109]
	v_mfma_f32_16x16x32_bf16 v[94:97], v[162:165], v[208:211], v[94:97]
	v_mfma_f32_16x16x32_bf16 v[90:93], v[178:181], v[208:211], v[90:93]
	v_mfma_f32_16x16x32_bf16 v[78:81], v[162:165], v[216:219], v[78:81]
	v_mfma_f32_16x16x32_bf16 v[74:77], v[178:181], v[216:219], v[74:77]
	v_mfma_f32_16x16x32_bf16 v[70:73], v[162:165], v[240:243], v[70:73]
	v_mfma_f32_16x16x32_bf16 v[66:69], v[178:181], v[240:243], v[66:69]
	s_barrier
; #define GAS __attribute__((address_space(1)))
; #define PG8_STAGE(bufoff, gbase, voff) do { _Pragma("unroll") for (int _i = 0; _i < 2; ++_i) \
;         __builtin_amdgcn_global_load_lds((const unsigned*)((const char*)(gbase) + (voff)[_i]), (LAS unsigned*)(lds + (bufoff) + ldsw + _i * 8192), 16, 0, 0); } while (0)
; #define PG8_LDA(dst, b, h) do { _Pragma("unroll") for (int m = 0; m < 4; ++m) _Pragma("unroll") for (int k = 0; k < 2; ++k) dst[m][k] = *(const LAS bf16x8*)(lds + PG8_SA(b, h) + aoff + m * 2048 + k * 1024); } while (0)
; #define PG8_MMA(ai, bj, At, Bt) do { __builtin_amdgcn_s_setprio(1); _Pragma("unroll") for (int m = 0; m < 4; ++m) _Pragma("unroll") for (int n = 0; n < 2; ++n) _Pragma("unroll") for (int k = 0; k < 2; ++k) \
;         acc[ai][bj][m][n] = __builtin_amdgcn_mfma_f32_16x16x32_bf16(Bt[n][k], At[m][k], acc[ai][bj][m][n], 0, 0, 0); __builtin_amdgcn_s_setprio(0); } while (0)
; #define PG8_WAIT_V(n) asm volatile("s_waitcnt vmcnt(" #n ")" ::: "memory")
; #define PG8_WAIT_L(n) asm volatile("s_waitcnt lgkmcnt(" #n ")" ::: "memory")
; #define PG8_BAR __builtin_amdgcn_s_barrier()
; #define PG8_SCHED __builtin_amdgcn_sched_barrier(0)
; template <class Epi, bool ALIGN_EPI>
; __device__ __forceinline__ void gemm_phase(LAS unsigned char* lds, const int tid, const Gemm g, const StaticOrder& S, const Epi& E) {
;     ...
;             PG8_LDA(At, 1, 1); PG8_STAGE(PG8_SB(1, 0), b3, voffB); PG8_STAGE(PG8_SB(1, 1), b3 + hstepB, voffB); PG8_STAGE(PG8_SA(1, 0), a3, voffA);
;             PG8_WAIT_V(8); PG8_WAIT_L(0); PG8_BAR; PG8_MMA(1, 0, At, B0); PG8_MMA(1, 1, At, B1); PG8_BAR; PG8_SCHED;
;         }
;     __device__ __forceinline__ void operator()(const f32x4 (&acc)[2][2][4][2], const Unit& u, int wr, int wc, int fr, int fq) const {
;     ...
;         } else {
;             const int col0 = colt - ZW + wc * 32 + 8 * fq;
;             f32x4 bv[2][2];
; #pragma unroll
;             for (int bj = 0; bj < 2; ++bj)
; #pragma unroll
;                 for (int n = 0; n < 2; ++n) bv[bj][n] = *(const GAS f32x4*)(bgate + col0 + bj * HALF + 4 * n);
	s_add_i32 s24, s49, s27
	v_lshl_add_u64 v[170:171], v[170:171], 0, s[42:43]
	s_mov_b32 m0, s24
	ds_read_b128 v[182:185], v176 offset:49152
	ds_read_b128 v[186:189], v176 offset:50176
	ds_read_b128 v[190:193], v176 offset:51200
	ds_read_b128 v[208:211], v176 offset:52224
	ds_read_b128 v[212:215], v176 offset:53248
	ds_read_b128 v[216:219], v176 offset:54272
	ds_read_b128 v[220:223], v176 offset:55296
	ds_read_b128 v[240:243], v176 offset:56320
	global_load_lds_dwordx4 v[170:171], off
	s_add_i32 m0, s24, 0x2000
	s_add_u32 s22, s22, 0x80080
	v_lshl_add_u64 v[170:171], v[194:195], 0, s[42:43]
	s_addc_u32 s23, s23, 0
	s_add_i32 s24, s52, s27
	global_load_lds_dwordx4 v[170:171], off
	v_lshl_add_u64 v[170:171], s[22:23], 0, v[148:149]
	s_mov_b32 m0, s24
	s_nop 0
	global_load_lds_dwordx4 v[170:171], off
	v_lshl_add_u64 v[170:171], s[22:23], 0, v[152:153]
	s_add_i32 m0, s24, 0x2000
	s_nop 0
	global_load_lds_dwordx4 v[170:171], off
	s_nop 0
	s_waitcnt vmcnt(4)
	s_waitcnt lgkmcnt(0)
	s_barrier
	v_mfma_f32_16x16x32_bf16 v[62:65], v[130:133], v[182:185], v[62:65]
	v_mfma_f32_16x16x32_bf16 v[58:61], v[138:141], v[182:185], v[58:61]
	v_mfma_f32_16x16x32_bf16 v[54:57], v[130:133], v[190:193], v[54:57]
	v_mfma_f32_16x16x32_bf16 v[50:53], v[138:141], v[190:193], v[50:53]
	v_mfma_f32_16x16x32_bf16 v[38:41], v[130:133], v[212:215], v[38:41]
	v_mfma_f32_16x16x32_bf16 v[34:37], v[138:141], v[212:215], v[34:37]
	v_mfma_f32_16x16x32_bf16 v[22:25], v[130:133], v[220:223], v[22:25]
	v_mfma_f32_16x16x32_bf16 v[18:21], v[138:141], v[220:223], v[18:21]
	v_mfma_f32_16x16x32_bf16 v[62:65], v[134:137], v[186:189], v[62:65]
	v_mfma_f32_16x16x32_bf16 v[58:61], v[142:145], v[186:189], v[58:61]
	v_mfma_f32_16x16x32_bf16 v[54:57], v[134:137], v[208:211], v[54:57]
	v_mfma_f32_16x16x32_bf16 v[50:53], v[142:145], v[208:211], v[50:53]
	v_mfma_f32_16x16x32_bf16 v[38:41], v[134:137], v[216:219], v[38:41]
	v_mfma_f32_16x16x32_bf16 v[34:37], v[142:145], v[216:219], v[34:37]
	v_mfma_f32_16x16x32_bf16 v[22:25], v[134:137], v[240:243], v[22:25]
	v_mfma_f32_16x16x32_bf16 v[18:21], v[142:145], v[240:243], v[18:21]
	v_mfma_f32_16x16x32_bf16 v[46:49], v[158:161], v[182:185], v[46:49]
	v_mfma_f32_16x16x32_bf16 v[42:45], v[166:169], v[182:185], v[42:45]
	v_mfma_f32_16x16x32_bf16 v[30:33], v[158:161], v[190:193], v[30:33]
	v_mfma_f32_16x16x32_bf16 v[26:29], v[166:169], v[190:193], v[26:29]
	v_mfma_f32_16x16x32_bf16 v[14:17], v[158:161], v[212:215], v[14:17]
	v_mfma_f32_16x16x32_bf16 v[10:13], v[166:169], v[212:215], v[10:13]
	v_mfma_f32_16x16x32_bf16 v[6:9], v[158:161], v[220:223], v[6:9]
	v_mfma_f32_16x16x32_bf16 v[2:5], v[166:169], v[220:223], v[2:5]
	v_mfma_f32_16x16x32_bf16 v[46:49], v[162:165], v[186:189], v[46:49]
	v_mfma_f32_16x16x32_bf16 v[42:45], v[178:181], v[186:189], v[42:45]
	v_mfma_f32_16x16x32_bf16 v[30:33], v[162:165], v[208:211], v[30:33]
	v_mfma_f32_16x16x32_bf16 v[26:29], v[178:181], v[208:211], v[26:29]
	v_mfma_f32_16x16x32_bf16 v[14:17], v[162:165], v[216:219], v[14:17]
	v_mfma_f32_16x16x32_bf16 v[10:13], v[178:181], v[216:219], v[10:13]
	v_mfma_f32_16x16x32_bf16 v[6:9], v[162:165], v[240:243], v[6:9]
	v_mfma_f32_16x16x32_bf16 v[2:5], v[178:181], v[240:243], v[2:5]
	s_barrier
	s_add_i32 s19, s19, 2
	s_add_u32 s11, s11, 0x100
	s_addc_u32 s13, s13, 0
	s_add_u32 s20, s20, 0x100
	s_addc_u32 s21, s21, 0
	s_cmp_gt_u32 s19, 29
	s_cbranch_scc0 .LBB0_667
	s_lshl_b32 s11, s41, 8
	s_cmp_gt_i32 s41, 16
	s_cbranch_scc0 .Lwin_nobias
	v_add_u32_e32 v0, s11, v175
	v_lshl_add_u64 v[134:135], v[0:1], 2, s[6:7]
	global_load_dwordx4 v[138:141], v[134:135], off offset:16
	global_load_dwordx4 v[142:145], v[134:135], off
	global_load_dwordx4 v[130:133], v[134:135], off offset:528
	s_nop 0
	global_load_dwordx4 v[134:137], v[134:135], off offset:512
